# deferred-barrier epilogue overlap + hand-written PLE_1 epilogue (deep load pipeline, packed f32)
# baseline (speedup 1.0000x reference)
; __device__ __forceinline__ float sigmoidf_(float v) { return __builtin_amdgcn_rcpf(1.0f + __expf(-v)); }
;     template <int KIND> __device__ __forceinline__ void run(f32x4 (&acc)[2][2][4][2], const Unit& u, int tid_in) const {
;     ...
;             const bf16_t* xsrc = mg; float rs[8]; get_rs(u, wr, fr, rs);
; #pragma unroll
;             for (int ai = 0; ai < 2; ++ai)
; #pragma unroll
;                 for (int mh = 0; mh < 2; ++mh) { u32x4 xv[2][2], pv[2][2];
; #pragma unroll
;                     for (int ml = 0; ml < 2; ++ml) { const int m = mh * 2 + ml; int row = rbase + ai * 128 + m * 16; asm volatile("" : "+v"(row));
; #pragma unroll
;                         for (int bj = 0; bj < 2; ++bj) { xv[ml][bj] = *(const u32x4*)(xsrc + (size_t)row * 1024 + u.pn * 256 + bj * 128 + cl); pv[ml][bj] = scr[((ai * 4 + m) * 2 + bj) * 512 + tid]; } }
; #pragma unroll
;                     for (int ml = 0; ml < 2; ++ml) { const int m = mh * 2 + ml; int row = rbase + ai * 128 + m * 16; asm volatile("" : "+v"(row)); float ss = 0.f; const float r = rs[ai * 4 + m];
; #pragma unroll
;                         for (int bj = 0; bj < 2; ++bj) { const size_t off = (size_t)row * 1024 + u.pn * 256 + bj * 128 + cl; f32x4 a = acc[ai][bj][m][0], b = acc[ai][bj][m][1], p0, p1, x0, x1;
;                             unpack8(pv[ml][bj], p0, p1); unpack8(xv[ml][bj], x0, x1);
; #pragma unroll
;                             for (int j = 0; j < 4; ++j) { a[j] = sigmoidf_(a[j] * r) * p0[j]; b[j] = sigmoidf_(b[j] * r) * p1[j]; }
;                             const f32x4 o0 = x0 + a, o1 = x1 + b;
;                             *(u32x4*)(xb0 + off) = pack8(o0, o1);
;                             { u32x2 w8; w8.x = pack4_fp8(o0[0], o0[1], o0[2], o0[3]); w8.y = pack4_fp8(o1[0], o1[1], o1[2], o1[3]); *(u32x2*)((unsigned char*)zb + (size_t)row * (ZW * 2) + u.pn * 256 + bj * 128 + cl) = w8; }
;                             ss += (o0[0] * o0[0] + o0[1] * o0[1]) + (o0[2] * o0[2] + o0[3] * o0[3]) + (o1[0] * o1[0] + o1[1] * o1[1]) + (o1[2] * o1[2] + o1[3] * o1[3]); }
;                         ss += __shfl_xor(ss, 16); ss += __shfl_xor(ss, 32);
;                         if (fq == 0) ssq0[((size_t)u.pn * T_TOK + row) * 4 + wc] = ss; }
.Ldb_PLE1_exit:
	s_lshl_b32 s2, s33, 17
	s_and_b32 s2, s2, 0x20000
	s_add_u32 s22, s43, s2
	s_addc_u32 s23, s50, 0
	v_readfirstlane_b32 s4, v180
	s_bfe_u32 s53, s4, 0x20006
	s_lshl_b32 s5, s7, 8
	s_ashr_i32 s7, s4, 2
	s_andn2_b32 s7, s7, 63
	s_add_i32 s7, s7, s5
	s_lshl_b32 s5, s33, 10
	s_and_b32 s4, s4, 0xffffff00
	s_add_i32 s5, s5, s4
	v_and_b32_e32 v0, 15, v180
	v_or_b32_e32 v195, s7, v0
	v_lshl_add_u32 v0, v0, 2, s5
	v_add_u32_e32 v0, 0x20010, v0
	ds_read_b32 v250, v0
	ds_read_b32 v251, v0 offset:64
	ds_read_b32 v252, v0 offset:128
	ds_read_b32 v253, v0 offset:192
	ds_read_b32 v254, v0 offset:512
	ds_read_b32 v255, v0 offset:576
	ds_read_b32 v224, v0 offset:640
	ds_read_b32 v225, v0 offset:704
	v_bfe_u32 v226, v180, 4, 2
	v_lshlrev_b32_e32 v226, 3, v226
	v_lshl_or_b32 v226, s53, 5, v226
	s_lshl_b32 s2, s6, 8
	v_add_u32_e32 v226, s2, v226
	v_lshlrev_b32_e32 v183, 11, v195
	v_lshl_add_u32 v183, v226, 1, v183
	v_mad_u32_u24 v185, v195, s76, v226
	v_lshlrev_b32_e32 v184, 4, v180
	s_mov_b32 s4, s8
	s_mov_b32 s5, s9
	s_mov_b32 s24, s22
	s_mov_b32 s25, s23
	global_load_dwordx4 v[136:139], v183, s[4:5]
	global_load_dwordx4 v[144:147], v184, s[24:25]
	s_add_u32 s24, s24, 0x2000
	s_addc_u32 s25, s25, 0
	global_load_dwordx4 v[140:143], v183, s[4:5] offset:256
	global_load_dwordx4 v[148:151], v184, s[24:25]
	s_add_u32 s4, s8, 0x8000
	s_addc_u32 s5, s9, 0
	s_add_u32 s24, s22, 0x4000
	s_addc_u32 s25, s23, 0
	global_load_dwordx4 v[152:155], v183, s[4:5]
	global_load_dwordx4 v[164:167], v184, s[24:25]
	s_add_u32 s24, s24, 0x2000
	s_addc_u32 s25, s25, 0
	global_load_dwordx4 v[160:163], v183, s[4:5] offset:256
	global_load_dwordx4 v[172:175], v184, s[24:25]
	s_add_u32 s4, s8, 0x10000
	s_addc_u32 s5, s9, 0
	s_add_u32 s24, s22, 0x8000
	s_addc_u32 s25, s23, 0
	global_load_dwordx4 v[176:179], v183, s[4:5]
	global_load_dwordx4 v[200:203], v184, s[24:25]
	s_add_u32 s24, s24, 0x2000
	s_addc_u32 s25, s25, 0
	global_load_dwordx4 v[196:199], v183, s[4:5] offset:256
	global_load_dwordx4 v[204:207], v184, s[24:25]
	s_add_u32 s4, s8, 0x18000
	s_addc_u32 s5, s9, 0
	s_add_u32 s24, s22, 0xc000
	s_addc_u32 s25, s23, 0
	global_load_dwordx4 v[208:211], v183, s[4:5]
	global_load_dwordx4 v[216:219], v184, s[24:25]
	s_add_u32 s24, s24, 0x2000
	s_addc_u32 s25, s25, 0
	global_load_dwordx4 v[212:215], v183, s[4:5] offset:256
	global_load_dwordx4 v[220:223], v184, s[24:25]
	s_mov_b32 s2, 0xbfb8aa3b
	s_mov_b32 s74, 1.0
	s_waitcnt lgkmcnt(0)
	s_waitcnt vmcnt(12)
	v_mov_b32_e32 v226, v250
	s_mov_b32 s40, s12
	s_mov_b32 s41, s13
	s_mov_b32 s44, s10
	s_mov_b32 s45, s11
	v_pk_mul_f32 v[132:133], v[132:133], v[226:227] op_sel_hi:[1,0]
	v_pk_mul_f32 v[134:135], v[134:135], v[226:227] op_sel_hi:[1,0]
	v_pk_mul_f32 v[128:129], v[128:129], v[226:227] op_sel_hi:[1,0]
	v_pk_mul_f32 v[130:131], v[130:131], v[226:227] op_sel_hi:[1,0]
	v_pk_mul_f32 v[132:133], v[132:133], s[2:3] op_sel_hi:[1,0]
	v_pk_mul_f32 v[134:135], v[134:135], s[2:3] op_sel_hi:[1,0]
	v_pk_mul_f32 v[128:129], v[128:129], s[2:3] op_sel_hi:[1,0]
	v_pk_mul_f32 v[130:131], v[130:131], s[2:3] op_sel_hi:[1,0]
	v_exp_f32_e32 v132, v132
	v_exp_f32_e32 v133, v133
	v_exp_f32_e32 v134, v134
	v_exp_f32_e32 v135, v135
	v_exp_f32_e32 v128, v128
	v_exp_f32_e32 v129, v129
	v_exp_f32_e32 v130, v130
	v_exp_f32_e32 v131, v131
	v_pk_add_f32 v[132:133], v[132:133], s[74:75] op_sel_hi:[1,0]
	v_pk_add_f32 v[134:135], v[134:135], s[74:75] op_sel_hi:[1,0]
	v_pk_add_f32 v[128:129], v[128:129], s[74:75] op_sel_hi:[1,0]
	v_pk_add_f32 v[130:131], v[130:131], s[74:75] op_sel_hi:[1,0]
	v_rcp_f32_e32 v132, v132
	v_rcp_f32_e32 v133, v133
	v_rcp_f32_e32 v134, v134
	v_rcp_f32_e32 v135, v135
	v_rcp_f32_e32 v128, v128
	v_rcp_f32_e32 v129, v129
	v_rcp_f32_e32 v130, v130
	v_rcp_f32_e32 v131, v131
	v_lshlrev_b32_e32 v234, 16, v136
	v_and_b32_e32 v235, 0xffff0000, v136
	v_lshlrev_b32_e32 v236, 16, v137
	v_and_b32_e32 v237, 0xffff0000, v137
	v_lshlrev_b32_e32 v238, 16, v138
	v_and_b32_e32 v239, 0xffff0000, v138
	v_lshlrev_b32_e32 v240, 16, v139
	v_and_b32_e32 v241, 0xffff0000, v139
	v_lshlrev_b32_e32 v242, 16, v144
	v_and_b32_e32 v243, 0xffff0000, v144
	v_lshlrev_b32_e32 v244, 16, v145
	v_and_b32_e32 v245, 0xffff0000, v145
	v_lshlrev_b32_e32 v246, 16, v146
	v_and_b32_e32 v247, 0xffff0000, v146
	v_lshlrev_b32_e32 v248, 16, v147
	v_and_b32_e32 v249, 0xffff0000, v147
	v_pk_fma_f32 v[132:133], v[132:133], v[242:243], v[234:235]
	v_pk_fma_f32 v[134:135], v[134:135], v[244:245], v[236:237]
	v_pk_fma_f32 v[128:129], v[128:129], v[246:247], v[238:239]
	v_pk_fma_f32 v[130:131], v[130:131], v[248:249], v[240:241]
	v_cvt_pk_bf16_f32 v234, v132, v133
	v_cvt_pk_bf16_f32 v235, v134, v135
	v_cvt_pk_bf16_f32 v236, v128, v129
	v_cvt_pk_bf16_f32 v237, v130, v131
	global_store_dwordx4 v183, v[234:237], s[40:41]
	v_cvt_pk_fp8_f32 v242, v132, v133
	v_cvt_pk_fp8_f32 v243, v128, v129
	v_cvt_pk_fp8_f32 v242, v134, v135 op_sel:[0,0,1]
	v_cvt_pk_fp8_f32 v243, v130, v131 op_sel:[0,0,1]
	v_pk_mul_f32 v[248:249], v[132:133], v[132:133]
	v_pk_fma_f32 v[248:249], v[134:135], v[134:135], v[248:249]
	v_pk_fma_f32 v[248:249], v[128:129], v[128:129], v[248:249]
	v_pk_fma_f32 v[248:249], v[130:131], v[130:131], v[248:249]
	global_store_dwordx2 v185, v[242:243], s[44:45]
	v_add_f32_e32 v195, v248, v249
	v_pk_mul_f32 v[124:125], v[124:125], v[226:227] op_sel_hi:[1,0]
	v_pk_mul_f32 v[126:127], v[126:127], v[226:227] op_sel_hi:[1,0]
	v_pk_mul_f32 v[120:121], v[120:121], v[226:227] op_sel_hi:[1,0]
	v_pk_mul_f32 v[122:123], v[122:123], v[226:227] op_sel_hi:[1,0]
	v_pk_mul_f32 v[124:125], v[124:125], s[2:3] op_sel_hi:[1,0]
	v_pk_mul_f32 v[126:127], v[126:127], s[2:3] op_sel_hi:[1,0]
; __device__ __forceinline__ float sigmoidf_(float v) { return __builtin_amdgcn_rcpf(1.0f + __expf(-v)); }
; __device__ __forceinline__ u32x4 pack8(const f32x4 a, const f32x4 b) { u32x4 w; w.x = cvt_pk_bf16(a[0], a[1]); w.y = cvt_pk_bf16(a[2], a[3]); w.z = cvt_pk_bf16(b[0], b[1]); w.w = cvt_pk_bf16(b[2], b[3]); return w; }
;     template <int KIND> __device__ __forceinline__ void run(f32x4 (&acc)[2][2][4][2], const Unit& u, int tid_in) const {
;     ...
;                     for (int ml = 0; ml < 2; ++ml) { const int m = mh * 2 + ml; int row = rbase + ai * 128 + m * 16; asm volatile("" : "+v"(row));
; #pragma unroll
;                         for (int bj = 0; bj < 2; ++bj) { xv[ml][bj] = *(const u32x4*)(xsrc + (size_t)row * 1024 + u.pn * 256 + bj * 128 + cl); pv[ml][bj] = scr[((ai * 4 + m) * 2 + bj) * 512 + tid]; } }
; #pragma unroll
;                     for (int ml = 0; ml < 2; ++ml) { const int m = mh * 2 + ml; int row = rbase + ai * 128 + m * 16; asm volatile("" : "+v"(row)); float ss = 0.f; const float r = rs[ai * 4 + m];
; #pragma unroll
;                         for (int bj = 0; bj < 2; ++bj) { const size_t off = (size_t)row * 1024 + u.pn * 256 + bj * 128 + cl; f32x4 a = acc[ai][bj][m][0], b = acc[ai][bj][m][1], p0, p1, x0, x1;
;                             unpack8(pv[ml][bj], p0, p1); unpack8(xv[ml][bj], x0, x1);
; #pragma unroll
;                             for (int j = 0; j < 4; ++j) { a[j] = sigmoidf_(a[j] * r) * p0[j]; b[j] = sigmoidf_(b[j] * r) * p1[j]; }
;                             const f32x4 o0 = x0 + a, o1 = x1 + b;
;                             *(u32x4*)(xb0 + off) = pack8(o0, o1);
;                             { u32x2 w8; w8.x = pack4_fp8(o0[0], o0[1], o0[2], o0[3]); w8.y = pack4_fp8(o1[0], o1[1], o1[2], o1[3]); *(u32x2*)((unsigned char*)zb + (size_t)row * (ZW * 2) + u.pn * 256 + bj * 128 + cl) = w8; }
;                             ss += (o0[0] * o0[0] + o0[1] * o0[1]) + (o0[2] * o0[2] + o0[3] * o0[3]) + (o1[0] * o1[0] + o1[1] * o1[1]) + (o1[2] * o1[2] + o1[3] * o1[3]); }
;                         ss += __shfl_xor(ss, 16); ss += __shfl_xor(ss, 32);
;                         if (fq == 0) ssq0[((size_t)u.pn * T_TOK + row) * 4 + wc] = ss; }
	v_pk_mul_f32 v[120:121], v[120:121], s[2:3] op_sel_hi:[1,0]
	v_pk_mul_f32 v[122:123], v[122:123], s[2:3] op_sel_hi:[1,0]
	v_exp_f32_e32 v124, v124
	v_exp_f32_e32 v125, v125
	v_exp_f32_e32 v126, v126
	v_exp_f32_e32 v127, v127
	v_exp_f32_e32 v120, v120
	v_exp_f32_e32 v121, v121
	v_exp_f32_e32 v122, v122
	v_exp_f32_e32 v123, v123
	v_pk_add_f32 v[124:125], v[124:125], s[74:75] op_sel_hi:[1,0]
	v_pk_add_f32 v[126:127], v[126:127], s[74:75] op_sel_hi:[1,0]
	v_pk_add_f32 v[120:121], v[120:121], s[74:75] op_sel_hi:[1,0]
	v_pk_add_f32 v[122:123], v[122:123], s[74:75] op_sel_hi:[1,0]
	v_rcp_f32_e32 v124, v124
	v_rcp_f32_e32 v125, v125
	v_rcp_f32_e32 v126, v126
	v_rcp_f32_e32 v127, v127
	v_rcp_f32_e32 v120, v120
	v_rcp_f32_e32 v121, v121
	v_rcp_f32_e32 v122, v122
	v_rcp_f32_e32 v123, v123
	v_lshlrev_b32_e32 v234, 16, v140
	v_and_b32_e32 v235, 0xffff0000, v140
	v_lshlrev_b32_e32 v236, 16, v141
	v_and_b32_e32 v237, 0xffff0000, v141
	v_lshlrev_b32_e32 v238, 16, v142
	v_and_b32_e32 v239, 0xffff0000, v142
	v_lshlrev_b32_e32 v240, 16, v143
	v_and_b32_e32 v241, 0xffff0000, v143
	v_lshlrev_b32_e32 v242, 16, v148
	v_and_b32_e32 v243, 0xffff0000, v148
	v_lshlrev_b32_e32 v244, 16, v149
	v_and_b32_e32 v245, 0xffff0000, v149
	v_lshlrev_b32_e32 v246, 16, v150
	v_and_b32_e32 v247, 0xffff0000, v150
	v_lshlrev_b32_e32 v248, 16, v151
	v_and_b32_e32 v249, 0xffff0000, v151
	v_pk_fma_f32 v[124:125], v[124:125], v[242:243], v[234:235]
	v_pk_fma_f32 v[126:127], v[126:127], v[244:245], v[236:237]
	v_pk_fma_f32 v[120:121], v[120:121], v[246:247], v[238:239]
	v_pk_fma_f32 v[122:123], v[122:123], v[248:249], v[240:241]
	v_cvt_pk_bf16_f32 v234, v124, v125
	v_cvt_pk_bf16_f32 v235, v126, v127
	v_cvt_pk_bf16_f32 v236, v120, v121
	v_cvt_pk_bf16_f32 v237, v122, v123
	global_store_dwordx4 v183, v[234:237], s[40:41] offset:256
	v_cvt_pk_fp8_f32 v242, v124, v125
	v_cvt_pk_fp8_f32 v243, v120, v121
	v_cvt_pk_fp8_f32 v242, v126, v127 op_sel:[0,0,1]
	v_cvt_pk_fp8_f32 v243, v122, v123 op_sel:[0,0,1]
	v_pk_mul_f32 v[248:249], v[124:125], v[124:125]
	v_pk_fma_f32 v[248:249], v[126:127], v[126:127], v[248:249]
	v_pk_fma_f32 v[248:249], v[120:121], v[120:121], v[248:249]
	v_pk_fma_f32 v[248:249], v[122:123], v[122:123], v[248:249]
	global_store_dwordx2 v185, v[242:243], s[44:45] offset:128
	v_add_f32_e32 v0, v248, v249
	v_add_f32_e32 v250, v195, v0
	s_add_u32 s4, s8, 0x40000
	s_addc_u32 s5, s9, 0
	s_add_u32 s24, s22, 0x10000
	s_addc_u32 s25, s23, 0
	global_load_dwordx4 v[136:139], v183, s[4:5]
	global_load_dwordx4 v[144:147], v184, s[24:25]
	s_add_u32 s24, s24, 0x2000
	s_addc_u32 s25, s25, 0
	global_load_dwordx4 v[140:143], v183, s[4:5] offset:256
	global_load_dwordx4 v[148:151], v184, s[24:25]
	s_add_u32 s4, s8, 0x48000
	s_addc_u32 s5, s9, 0
	s_add_u32 s24, s22, 0x14000
	s_addc_u32 s25, s23, 0
	global_load_dwordx4 v[132:135], v183, s[4:5]
	global_load_dwordx4 v[124:127], v184, s[24:25]
	s_add_u32 s24, s24, 0x2000
	s_addc_u32 s25, s25, 0
	global_load_dwordx4 v[128:131], v183, s[4:5] offset:256
	global_load_dwordx4 v[120:123], v184, s[24:25]
	s_waitcnt vmcnt(20)
	v_mov_b32_e32 v226, v251
	s_add_u32 s40, s12, 0x8000
	s_addc_u32 s41, s13, 0
	s_add_u32 s44, s10, 0x16000
	s_addc_u32 s45, s11, 0
	v_pk_mul_f32 v[116:117], v[116:117], v[226:227] op_sel_hi:[1,0]
	v_pk_mul_f32 v[118:119], v[118:119], v[226:227] op_sel_hi:[1,0]
	v_pk_mul_f32 v[112:113], v[112:113], v[226:227] op_sel_hi:[1,0]
	v_pk_mul_f32 v[114:115], v[114:115], v[226:227] op_sel_hi:[1,0]
	v_pk_mul_f32 v[116:117], v[116:117], s[2:3] op_sel_hi:[1,0]
	v_pk_mul_f32 v[118:119], v[118:119], s[2:3] op_sel_hi:[1,0]
	v_pk_mul_f32 v[112:113], v[112:113], s[2:3] op_sel_hi:[1,0]
	v_pk_mul_f32 v[114:115], v[114:115], s[2:3] op_sel_hi:[1,0]
	v_exp_f32_e32 v116, v116
	v_exp_f32_e32 v117, v117
	v_exp_f32_e32 v118, v118
	v_exp_f32_e32 v119, v119
	v_exp_f32_e32 v112, v112
	v_exp_f32_e32 v113, v113
	v_exp_f32_e32 v114, v114
	v_exp_f32_e32 v115, v115
	v_pk_add_f32 v[116:117], v[116:117], s[74:75] op_sel_hi:[1,0]
	v_pk_add_f32 v[118:119], v[118:119], s[74:75] op_sel_hi:[1,0]
	v_pk_add_f32 v[112:113], v[112:113], s[74:75] op_sel_hi:[1,0]
	v_pk_add_f32 v[114:115], v[114:115], s[74:75] op_sel_hi:[1,0]
	v_rcp_f32_e32 v116, v116
	v_rcp_f32_e32 v117, v117
	v_rcp_f32_e32 v118, v118
	v_rcp_f32_e32 v119, v119
	v_rcp_f32_e32 v112, v112
	v_rcp_f32_e32 v113, v113
	v_rcp_f32_e32 v114, v114
	v_rcp_f32_e32 v115, v115
	v_lshlrev_b32_e32 v234, 16, v152
	v_and_b32_e32 v235, 0xffff0000, v152
	v_lshlrev_b32_e32 v236, 16, v153
	v_and_b32_e32 v237, 0xffff0000, v153
	v_lshlrev_b32_e32 v238, 16, v154
	v_and_b32_e32 v239, 0xffff0000, v154
	v_lshlrev_b32_e32 v240, 16, v155
	v_and_b32_e32 v241, 0xffff0000, v155
	v_lshlrev_b32_e32 v242, 16, v164
	v_and_b32_e32 v243, 0xffff0000, v164
	v_lshlrev_b32_e32 v244, 16, v165
	v_and_b32_e32 v245, 0xffff0000, v165
	v_lshlrev_b32_e32 v246, 16, v166
	v_and_b32_e32 v247, 0xffff0000, v166
	v_lshlrev_b32_e32 v248, 16, v167
	v_and_b32_e32 v249, 0xffff0000, v167
	v_pk_fma_f32 v[116:117], v[116:117], v[242:243], v[234:235]
	v_pk_fma_f32 v[118:119], v[118:119], v[244:245], v[236:237]
	v_pk_fma_f32 v[112:113], v[112:113], v[246:247], v[238:239]
	v_pk_fma_f32 v[114:115], v[114:115], v[248:249], v[240:241]
	v_cvt_pk_bf16_f32 v234, v116, v117
	v_cvt_pk_bf16_f32 v235, v118, v119
	v_cvt_pk_bf16_f32 v236, v112, v113
	v_cvt_pk_bf16_f32 v237, v114, v115
	global_store_dwordx4 v183, v[234:237], s[40:41]
	v_cvt_pk_fp8_f32 v242, v116, v117
	v_cvt_pk_fp8_f32 v243, v112, v113
	v_cvt_pk_fp8_f32 v242, v118, v119 op_sel:[0,0,1]
	v_cvt_pk_fp8_f32 v243, v114, v115 op_sel:[0,0,1]
	v_pk_mul_f32 v[248:249], v[116:117], v[116:117]
	v_pk_fma_f32 v[248:249], v[118:119], v[118:119], v[248:249]
; __device__ __forceinline__ float sigmoidf_(float v) { return __builtin_amdgcn_rcpf(1.0f + __expf(-v)); }
; __device__ __forceinline__ u32x4 pack8(const f32x4 a, const f32x4 b) { u32x4 w; w.x = cvt_pk_bf16(a[0], a[1]); w.y = cvt_pk_bf16(a[2], a[3]); w.z = cvt_pk_bf16(b[0], b[1]); w.w = cvt_pk_bf16(b[2], b[3]); return w; }
; __device__ __forceinline__ void unpack8(const u32x4 w, f32x4& a, f32x4& b) { a[0] = bf_lo(w.x); a[1] = bf_hi(w.x); a[2] = bf_lo(w.y); a[3] = bf_hi(w.y); b[0] = bf_lo(w.z); b[1] = bf_hi(w.z); b[2] = bf_lo(w.w); b[3] = bf_hi(w.w); }
; __device__ __forceinline__ unsigned pack4_fp8(float a, float b, float c, float d) { unsigned w = 0u; w = __builtin_amdgcn_cvt_pk_fp8_f32(a, b, w, false); w = __builtin_amdgcn_cvt_pk_fp8_f32(c, d, w, true); return w; }
;     template <int KIND> __device__ __forceinline__ void run(f32x4 (&acc)[2][2][4][2], const Unit& u, int tid_in) const {
;     ...
;                     for (int ml = 0; ml < 2; ++ml) { const int m = mh * 2 + ml; int row = rbase + ai * 128 + m * 16; asm volatile("" : "+v"(row)); float ss = 0.f; const float r = rs[ai * 4 + m];
; #pragma unroll
;                         for (int bj = 0; bj < 2; ++bj) { const size_t off = (size_t)row * 1024 + u.pn * 256 + bj * 128 + cl; f32x4 a = acc[ai][bj][m][0], b = acc[ai][bj][m][1], p0, p1, x0, x1;
;                             unpack8(pv[ml][bj], p0, p1); unpack8(xv[ml][bj], x0, x1);
; #pragma unroll
;                             for (int j = 0; j < 4; ++j) { a[j] = sigmoidf_(a[j] * r) * p0[j]; b[j] = sigmoidf_(b[j] * r) * p1[j]; }
;                             const f32x4 o0 = x0 + a, o1 = x1 + b;
;                             *(u32x4*)(xb0 + off) = pack8(o0, o1);
;                             { u32x2 w8; w8.x = pack4_fp8(o0[0], o0[1], o0[2], o0[3]); w8.y = pack4_fp8(o1[0], o1[1], o1[2], o1[3]); *(u32x2*)((unsigned char*)zb + (size_t)row * (ZW * 2) + u.pn * 256 + bj * 128 + cl) = w8; }
;                             ss += (o0[0] * o0[0] + o0[1] * o0[1]) + (o0[2] * o0[2] + o0[3] * o0[3]) + (o1[0] * o1[0] + o1[1] * o1[1]) + (o1[2] * o1[2] + o1[3] * o1[3]); }
;                         ss += __shfl_xor(ss, 16); ss += __shfl_xor(ss, 32);
;                         if (fq == 0) ssq0[((size_t)u.pn * T_TOK + row) * 4 + wc] = ss; }
	v_pk_fma_f32 v[248:249], v[112:113], v[112:113], v[248:249]
	v_pk_fma_f32 v[248:249], v[114:115], v[114:115], v[248:249]
	global_store_dwordx2 v185, v[242:243], s[44:45]
	v_add_f32_e32 v195, v248, v249
	v_pk_mul_f32 v[108:109], v[108:109], v[226:227] op_sel_hi:[1,0]
	v_pk_mul_f32 v[110:111], v[110:111], v[226:227] op_sel_hi:[1,0]
	v_pk_mul_f32 v[104:105], v[104:105], v[226:227] op_sel_hi:[1,0]
	v_pk_mul_f32 v[106:107], v[106:107], v[226:227] op_sel_hi:[1,0]
	v_pk_mul_f32 v[108:109], v[108:109], s[2:3] op_sel_hi:[1,0]
	v_pk_mul_f32 v[110:111], v[110:111], s[2:3] op_sel_hi:[1,0]
	v_pk_mul_f32 v[104:105], v[104:105], s[2:3] op_sel_hi:[1,0]
	v_pk_mul_f32 v[106:107], v[106:107], s[2:3] op_sel_hi:[1,0]
	v_exp_f32_e32 v108, v108
	v_exp_f32_e32 v109, v109
	v_exp_f32_e32 v110, v110
	v_exp_f32_e32 v111, v111
	v_exp_f32_e32 v104, v104
	v_exp_f32_e32 v105, v105
	v_exp_f32_e32 v106, v106
	v_exp_f32_e32 v107, v107
	v_pk_add_f32 v[108:109], v[108:109], s[74:75] op_sel_hi:[1,0]
	v_pk_add_f32 v[110:111], v[110:111], s[74:75] op_sel_hi:[1,0]
	v_pk_add_f32 v[104:105], v[104:105], s[74:75] op_sel_hi:[1,0]
	v_pk_add_f32 v[106:107], v[106:107], s[74:75] op_sel_hi:[1,0]
	v_rcp_f32_e32 v108, v108
	v_rcp_f32_e32 v109, v109
	v_rcp_f32_e32 v110, v110
	v_rcp_f32_e32 v111, v111
	v_rcp_f32_e32 v104, v104
	v_rcp_f32_e32 v105, v105
	v_rcp_f32_e32 v106, v106
	v_rcp_f32_e32 v107, v107
	v_lshlrev_b32_e32 v234, 16, v160
	v_and_b32_e32 v235, 0xffff0000, v160
	v_lshlrev_b32_e32 v236, 16, v161
	v_and_b32_e32 v237, 0xffff0000, v161
	v_lshlrev_b32_e32 v238, 16, v162
	v_and_b32_e32 v239, 0xffff0000, v162
	v_lshlrev_b32_e32 v240, 16, v163
	v_and_b32_e32 v241, 0xffff0000, v163
	v_lshlrev_b32_e32 v242, 16, v172
	v_and_b32_e32 v243, 0xffff0000, v172
	v_lshlrev_b32_e32 v244, 16, v173
	v_and_b32_e32 v245, 0xffff0000, v173
	v_lshlrev_b32_e32 v246, 16, v174
	v_and_b32_e32 v247, 0xffff0000, v174
	v_lshlrev_b32_e32 v248, 16, v175
	v_and_b32_e32 v249, 0xffff0000, v175
	v_pk_fma_f32 v[108:109], v[108:109], v[242:243], v[234:235]
	v_pk_fma_f32 v[110:111], v[110:111], v[244:245], v[236:237]
	v_pk_fma_f32 v[104:105], v[104:105], v[246:247], v[238:239]
	v_pk_fma_f32 v[106:107], v[106:107], v[248:249], v[240:241]
	v_cvt_pk_bf16_f32 v234, v108, v109
	v_cvt_pk_bf16_f32 v235, v110, v111
	v_cvt_pk_bf16_f32 v236, v104, v105
	v_cvt_pk_bf16_f32 v237, v106, v107
	global_store_dwordx4 v183, v[234:237], s[40:41] offset:256
	v_cvt_pk_fp8_f32 v242, v108, v109
	v_cvt_pk_fp8_f32 v243, v104, v105
	v_cvt_pk_fp8_f32 v242, v110, v111 op_sel:[0,0,1]
	v_cvt_pk_fp8_f32 v243, v106, v107 op_sel:[0,0,1]
	v_pk_mul_f32 v[248:249], v[108:109], v[108:109]
	v_pk_fma_f32 v[248:249], v[110:111], v[110:111], v[248:249]
	v_pk_fma_f32 v[248:249], v[104:105], v[104:105], v[248:249]
	v_pk_fma_f32 v[248:249], v[106:107], v[106:107], v[248:249]
	global_store_dwordx2 v185, v[242:243], s[44:45] offset:128
	v_add_f32_e32 v0, v248, v249
	v_add_f32_e32 v251, v195, v0
	s_add_u32 s4, s8, 0x50000
	s_addc_u32 s5, s9, 0
	s_add_u32 s24, s22, 0x18000
	s_addc_u32 s25, s23, 0
	global_load_dwordx4 v[152:155], v183, s[4:5]
	global_load_dwordx4 v[164:167], v184, s[24:25]
	s_add_u32 s24, s24, 0x2000
	s_addc_u32 s25, s25, 0
	global_load_dwordx4 v[160:163], v183, s[4:5] offset:256
	global_load_dwordx4 v[172:175], v184, s[24:25]
	s_add_u32 s4, s8, 0x58000
	s_addc_u32 s5, s9, 0
	s_add_u32 s24, s22, 0x1c000
	s_addc_u32 s25, s23, 0
	global_load_dwordx4 v[116:119], v183, s[4:5]
	global_load_dwordx4 v[108:111], v184, s[24:25]
	s_add_u32 s24, s24, 0x2000
	s_addc_u32 s25, s25, 0
	global_load_dwordx4 v[112:115], v183, s[4:5] offset:256
	global_load_dwordx4 v[104:107], v184, s[24:25]
	s_waitcnt vmcnt(28)
	v_mov_b32_e32 v226, v252
	s_add_u32 s40, s12, 0x10000
	s_addc_u32 s41, s13, 0
	s_add_u32 s44, s10, 0x2c000
	s_addc_u32 s45, s11, 0
	v_pk_mul_f32 v[100:101], v[100:101], v[226:227] op_sel_hi:[1,0]
	v_pk_mul_f32 v[102:103], v[102:103], v[226:227] op_sel_hi:[1,0]
	v_pk_mul_f32 v[96:97], v[96:97], v[226:227] op_sel_hi:[1,0]
	v_pk_mul_f32 v[98:99], v[98:99], v[226:227] op_sel_hi:[1,0]
	v_pk_mul_f32 v[100:101], v[100:101], s[2:3] op_sel_hi:[1,0]
	v_pk_mul_f32 v[102:103], v[102:103], s[2:3] op_sel_hi:[1,0]
	v_pk_mul_f32 v[96:97], v[96:97], s[2:3] op_sel_hi:[1,0]
	v_pk_mul_f32 v[98:99], v[98:99], s[2:3] op_sel_hi:[1,0]
	v_exp_f32_e32 v100, v100
	v_exp_f32_e32 v101, v101
	v_exp_f32_e32 v102, v102
	v_exp_f32_e32 v103, v103
	v_exp_f32_e32 v96, v96
	v_exp_f32_e32 v97, v97
	v_exp_f32_e32 v98, v98
	v_exp_f32_e32 v99, v99
	v_pk_add_f32 v[100:101], v[100:101], s[74:75] op_sel_hi:[1,0]
	v_pk_add_f32 v[102:103], v[102:103], s[74:75] op_sel_hi:[1,0]
	v_pk_add_f32 v[96:97], v[96:97], s[74:75] op_sel_hi:[1,0]
	v_pk_add_f32 v[98:99], v[98:99], s[74:75] op_sel_hi:[1,0]
	v_rcp_f32_e32 v100, v100
	v_rcp_f32_e32 v101, v101
	v_rcp_f32_e32 v102, v102
	v_rcp_f32_e32 v103, v103
	v_rcp_f32_e32 v96, v96
	v_rcp_f32_e32 v97, v97
	v_rcp_f32_e32 v98, v98
	v_rcp_f32_e32 v99, v99
	v_lshlrev_b32_e32 v234, 16, v176
	v_and_b32_e32 v235, 0xffff0000, v176
	v_lshlrev_b32_e32 v236, 16, v177
	v_and_b32_e32 v237, 0xffff0000, v177
	v_lshlrev_b32_e32 v238, 16, v178
	v_and_b32_e32 v239, 0xffff0000, v178
	v_lshlrev_b32_e32 v240, 16, v179
	v_and_b32_e32 v241, 0xffff0000, v179
	v_lshlrev_b32_e32 v242, 16, v200
	v_and_b32_e32 v243, 0xffff0000, v200
	v_lshlrev_b32_e32 v244, 16, v201
	v_and_b32_e32 v245, 0xffff0000, v201
	v_lshlrev_b32_e32 v246, 16, v202
	v_and_b32_e32 v247, 0xffff0000, v202
	v_lshlrev_b32_e32 v248, 16, v203
	v_and_b32_e32 v249, 0xffff0000, v203
	v_pk_fma_f32 v[100:101], v[100:101], v[242:243], v[234:235]
	v_pk_fma_f32 v[102:103], v[102:103], v[244:245], v[236:237]
	v_pk_fma_f32 v[96:97], v[96:97], v[246:247], v[238:239]
; __device__ __forceinline__ float sigmoidf_(float v) { return __builtin_amdgcn_rcpf(1.0f + __expf(-v)); }
; __device__ __forceinline__ u32x4 pack8(const f32x4 a, const f32x4 b) { u32x4 w; w.x = cvt_pk_bf16(a[0], a[1]); w.y = cvt_pk_bf16(a[2], a[3]); w.z = cvt_pk_bf16(b[0], b[1]); w.w = cvt_pk_bf16(b[2], b[3]); return w; }
; __device__ __forceinline__ void unpack8(const u32x4 w, f32x4& a, f32x4& b) { a[0] = bf_lo(w.x); a[1] = bf_hi(w.x); a[2] = bf_lo(w.y); a[3] = bf_hi(w.y); b[0] = bf_lo(w.z); b[1] = bf_hi(w.z); b[2] = bf_lo(w.w); b[3] = bf_hi(w.w); }
; __device__ __forceinline__ unsigned pack4_fp8(float a, float b, float c, float d) { unsigned w = 0u; w = __builtin_amdgcn_cvt_pk_fp8_f32(a, b, w, false); w = __builtin_amdgcn_cvt_pk_fp8_f32(c, d, w, true); return w; }
;     template <int KIND> __device__ __forceinline__ void run(f32x4 (&acc)[2][2][4][2], const Unit& u, int tid_in) const {
;     ...
;                     for (int ml = 0; ml < 2; ++ml) { const int m = mh * 2 + ml; int row = rbase + ai * 128 + m * 16; asm volatile("" : "+v"(row)); float ss = 0.f; const float r = rs[ai * 4 + m];
; #pragma unroll
;                         for (int bj = 0; bj < 2; ++bj) { const size_t off = (size_t)row * 1024 + u.pn * 256 + bj * 128 + cl; f32x4 a = acc[ai][bj][m][0], b = acc[ai][bj][m][1], p0, p1, x0, x1;
;                             unpack8(pv[ml][bj], p0, p1); unpack8(xv[ml][bj], x0, x1);
; #pragma unroll
;                             for (int j = 0; j < 4; ++j) { a[j] = sigmoidf_(a[j] * r) * p0[j]; b[j] = sigmoidf_(b[j] * r) * p1[j]; }
;                             const f32x4 o0 = x0 + a, o1 = x1 + b;
;                             *(u32x4*)(xb0 + off) = pack8(o0, o1);
;                             { u32x2 w8; w8.x = pack4_fp8(o0[0], o0[1], o0[2], o0[3]); w8.y = pack4_fp8(o1[0], o1[1], o1[2], o1[3]); *(u32x2*)((unsigned char*)zb + (size_t)row * (ZW * 2) + u.pn * 256 + bj * 128 + cl) = w8; }
;                             ss += (o0[0] * o0[0] + o0[1] * o0[1]) + (o0[2] * o0[2] + o0[3] * o0[3]) + (o1[0] * o1[0] + o1[1] * o1[1]) + (o1[2] * o1[2] + o1[3] * o1[3]); }
;                         ss += __shfl_xor(ss, 16); ss += __shfl_xor(ss, 32);
;                         if (fq == 0) ssq0[((size_t)u.pn * T_TOK + row) * 4 + wc] = ss; }
	v_pk_fma_f32 v[98:99], v[98:99], v[248:249], v[240:241]
	v_cvt_pk_bf16_f32 v234, v100, v101
	v_cvt_pk_bf16_f32 v235, v102, v103
	v_cvt_pk_bf16_f32 v236, v96, v97
	v_cvt_pk_bf16_f32 v237, v98, v99
	global_store_dwordx4 v183, v[234:237], s[40:41]
	v_cvt_pk_fp8_f32 v242, v100, v101
	v_cvt_pk_fp8_f32 v243, v96, v97
	v_cvt_pk_fp8_f32 v242, v102, v103 op_sel:[0,0,1]
	v_cvt_pk_fp8_f32 v243, v98, v99 op_sel:[0,0,1]
	v_pk_mul_f32 v[248:249], v[100:101], v[100:101]
	v_pk_fma_f32 v[248:249], v[102:103], v[102:103], v[248:249]
	v_pk_fma_f32 v[248:249], v[96:97], v[96:97], v[248:249]
	v_pk_fma_f32 v[248:249], v[98:99], v[98:99], v[248:249]
	global_store_dwordx2 v185, v[242:243], s[44:45]
	v_add_f32_e32 v195, v248, v249
	v_pk_mul_f32 v[92:93], v[92:93], v[226:227] op_sel_hi:[1,0]
	v_pk_mul_f32 v[94:95], v[94:95], v[226:227] op_sel_hi:[1,0]
	v_pk_mul_f32 v[88:89], v[88:89], v[226:227] op_sel_hi:[1,0]
	v_pk_mul_f32 v[90:91], v[90:91], v[226:227] op_sel_hi:[1,0]
	v_pk_mul_f32 v[92:93], v[92:93], s[2:3] op_sel_hi:[1,0]
	v_pk_mul_f32 v[94:95], v[94:95], s[2:3] op_sel_hi:[1,0]
	v_pk_mul_f32 v[88:89], v[88:89], s[2:3] op_sel_hi:[1,0]
	v_pk_mul_f32 v[90:91], v[90:91], s[2:3] op_sel_hi:[1,0]
	v_exp_f32_e32 v92, v92
	v_exp_f32_e32 v93, v93
	v_exp_f32_e32 v94, v94
	v_exp_f32_e32 v95, v95
	v_exp_f32_e32 v88, v88
	v_exp_f32_e32 v89, v89
	v_exp_f32_e32 v90, v90
	v_exp_f32_e32 v91, v91
	v_pk_add_f32 v[92:93], v[92:93], s[74:75] op_sel_hi:[1,0]
	v_pk_add_f32 v[94:95], v[94:95], s[74:75] op_sel_hi:[1,0]
	v_pk_add_f32 v[88:89], v[88:89], s[74:75] op_sel_hi:[1,0]
	v_pk_add_f32 v[90:91], v[90:91], s[74:75] op_sel_hi:[1,0]
	v_rcp_f32_e32 v92, v92
	v_rcp_f32_e32 v93, v93
	v_rcp_f32_e32 v94, v94
	v_rcp_f32_e32 v95, v95
	v_rcp_f32_e32 v88, v88
	v_rcp_f32_e32 v89, v89
	v_rcp_f32_e32 v90, v90
	v_rcp_f32_e32 v91, v91
	v_lshlrev_b32_e32 v234, 16, v196
	v_and_b32_e32 v235, 0xffff0000, v196
	v_lshlrev_b32_e32 v236, 16, v197
	v_and_b32_e32 v237, 0xffff0000, v197
	v_lshlrev_b32_e32 v238, 16, v198
	v_and_b32_e32 v239, 0xffff0000, v198
	v_lshlrev_b32_e32 v240, 16, v199
	v_and_b32_e32 v241, 0xffff0000, v199
	v_lshlrev_b32_e32 v242, 16, v204
	v_and_b32_e32 v243, 0xffff0000, v204
	v_lshlrev_b32_e32 v244, 16, v205
	v_and_b32_e32 v245, 0xffff0000, v205
	v_lshlrev_b32_e32 v246, 16, v206
	v_and_b32_e32 v247, 0xffff0000, v206
	v_lshlrev_b32_e32 v248, 16, v207
	v_and_b32_e32 v249, 0xffff0000, v207
	v_pk_fma_f32 v[92:93], v[92:93], v[242:243], v[234:235]
	v_pk_fma_f32 v[94:95], v[94:95], v[244:245], v[236:237]
	v_pk_fma_f32 v[88:89], v[88:89], v[246:247], v[238:239]
	v_pk_fma_f32 v[90:91], v[90:91], v[248:249], v[240:241]
	v_cvt_pk_bf16_f32 v234, v92, v93
	v_cvt_pk_bf16_f32 v235, v94, v95
	v_cvt_pk_bf16_f32 v236, v88, v89
	v_cvt_pk_bf16_f32 v237, v90, v91
	global_store_dwordx4 v183, v[234:237], s[40:41] offset:256
	v_cvt_pk_fp8_f32 v242, v92, v93
	v_cvt_pk_fp8_f32 v243, v88, v89
	v_cvt_pk_fp8_f32 v242, v94, v95 op_sel:[0,0,1]
	v_cvt_pk_fp8_f32 v243, v90, v91 op_sel:[0,0,1]
	v_pk_mul_f32 v[248:249], v[92:93], v[92:93]
	v_pk_fma_f32 v[248:249], v[94:95], v[94:95], v[248:249]
	v_pk_fma_f32 v[248:249], v[88:89], v[88:89], v[248:249]
	v_pk_fma_f32 v[248:249], v[90:91], v[90:91], v[248:249]
	global_store_dwordx2 v185, v[242:243], s[44:45] offset:128
	v_add_f32_e32 v0, v248, v249
	v_add_f32_e32 v252, v195, v0
	s_waitcnt vmcnt(28)
	v_mov_b32_e32 v226, v253
	s_add_u32 s40, s12, 0x18000
	s_addc_u32 s41, s13, 0
	s_add_u32 s44, s10, 0x42000
	s_addc_u32 s45, s11, 0
	v_pk_mul_f32 v[84:85], v[84:85], v[226:227] op_sel_hi:[1,0]
	v_pk_mul_f32 v[86:87], v[86:87], v[226:227] op_sel_hi:[1,0]
	v_pk_mul_f32 v[80:81], v[80:81], v[226:227] op_sel_hi:[1,0]
	v_pk_mul_f32 v[82:83], v[82:83], v[226:227] op_sel_hi:[1,0]
	v_pk_mul_f32 v[84:85], v[84:85], s[2:3] op_sel_hi:[1,0]
	v_pk_mul_f32 v[86:87], v[86:87], s[2:3] op_sel_hi:[1,0]
	v_pk_mul_f32 v[80:81], v[80:81], s[2:3] op_sel_hi:[1,0]
	v_pk_mul_f32 v[82:83], v[82:83], s[2:3] op_sel_hi:[1,0]
	v_exp_f32_e32 v84, v84
	v_exp_f32_e32 v85, v85
	v_exp_f32_e32 v86, v86
	v_exp_f32_e32 v87, v87
	v_exp_f32_e32 v80, v80
	v_exp_f32_e32 v81, v81
	v_exp_f32_e32 v82, v82
	v_exp_f32_e32 v83, v83
	v_pk_add_f32 v[84:85], v[84:85], s[74:75] op_sel_hi:[1,0]
	v_pk_add_f32 v[86:87], v[86:87], s[74:75] op_sel_hi:[1,0]
	v_pk_add_f32 v[80:81], v[80:81], s[74:75] op_sel_hi:[1,0]
	v_pk_add_f32 v[82:83], v[82:83], s[74:75] op_sel_hi:[1,0]
	v_rcp_f32_e32 v84, v84
	v_rcp_f32_e32 v85, v85
	v_rcp_f32_e32 v86, v86
	v_rcp_f32_e32 v87, v87
	v_rcp_f32_e32 v80, v80
	v_rcp_f32_e32 v81, v81
	v_rcp_f32_e32 v82, v82
	v_rcp_f32_e32 v83, v83
	v_lshlrev_b32_e32 v234, 16, v208
	v_and_b32_e32 v235, 0xffff0000, v208
	v_lshlrev_b32_e32 v236, 16, v209
	v_and_b32_e32 v237, 0xffff0000, v209
	v_lshlrev_b32_e32 v238, 16, v210
	v_and_b32_e32 v239, 0xffff0000, v210
	v_lshlrev_b32_e32 v240, 16, v211
	v_and_b32_e32 v241, 0xffff0000, v211
	v_lshlrev_b32_e32 v242, 16, v216
	v_and_b32_e32 v243, 0xffff0000, v216
	v_lshlrev_b32_e32 v244, 16, v217
	v_and_b32_e32 v245, 0xffff0000, v217
	v_lshlrev_b32_e32 v246, 16, v218
	v_and_b32_e32 v247, 0xffff0000, v218
	v_lshlrev_b32_e32 v248, 16, v219
	v_and_b32_e32 v249, 0xffff0000, v219
	v_pk_fma_f32 v[84:85], v[84:85], v[242:243], v[234:235]
	v_pk_fma_f32 v[86:87], v[86:87], v[244:245], v[236:237]
	v_pk_fma_f32 v[80:81], v[80:81], v[246:247], v[238:239]
	v_pk_fma_f32 v[82:83], v[82:83], v[248:249], v[240:241]
	v_cvt_pk_bf16_f32 v234, v84, v85
	v_cvt_pk_bf16_f32 v235, v86, v87
	v_cvt_pk_bf16_f32 v236, v80, v81
	v_cvt_pk_bf16_f32 v237, v82, v83
	global_store_dwordx4 v183, v[234:237], s[40:41]
	v_cvt_pk_fp8_f32 v242, v84, v85
	v_cvt_pk_fp8_f32 v243, v80, v81
	v_cvt_pk_fp8_f32 v242, v86, v87 op_sel:[0,0,1]
; __device__ __forceinline__ float sigmoidf_(float v) { return __builtin_amdgcn_rcpf(1.0f + __expf(-v)); }
; __device__ __forceinline__ u32x4 pack8(const f32x4 a, const f32x4 b) { u32x4 w; w.x = cvt_pk_bf16(a[0], a[1]); w.y = cvt_pk_bf16(a[2], a[3]); w.z = cvt_pk_bf16(b[0], b[1]); w.w = cvt_pk_bf16(b[2], b[3]); return w; }
; __device__ __forceinline__ void unpack8(const u32x4 w, f32x4& a, f32x4& b) { a[0] = bf_lo(w.x); a[1] = bf_hi(w.x); a[2] = bf_lo(w.y); a[3] = bf_hi(w.y); b[0] = bf_lo(w.z); b[1] = bf_hi(w.z); b[2] = bf_lo(w.w); b[3] = bf_hi(w.w); }
; __device__ __forceinline__ unsigned pack4_fp8(float a, float b, float c, float d) { unsigned w = 0u; w = __builtin_amdgcn_cvt_pk_fp8_f32(a, b, w, false); w = __builtin_amdgcn_cvt_pk_fp8_f32(c, d, w, true); return w; }
;     template <int KIND> __device__ __forceinline__ void run(f32x4 (&acc)[2][2][4][2], const Unit& u, int tid_in) const {
;     ...
;                     for (int ml = 0; ml < 2; ++ml) { const int m = mh * 2 + ml; int row = rbase + ai * 128 + m * 16; asm volatile("" : "+v"(row)); float ss = 0.f; const float r = rs[ai * 4 + m];
; #pragma unroll
;                         for (int bj = 0; bj < 2; ++bj) { const size_t off = (size_t)row * 1024 + u.pn * 256 + bj * 128 + cl; f32x4 a = acc[ai][bj][m][0], b = acc[ai][bj][m][1], p0, p1, x0, x1;
;                             unpack8(pv[ml][bj], p0, p1); unpack8(xv[ml][bj], x0, x1);
; #pragma unroll
;                             for (int j = 0; j < 4; ++j) { a[j] = sigmoidf_(a[j] * r) * p0[j]; b[j] = sigmoidf_(b[j] * r) * p1[j]; }
;                             const f32x4 o0 = x0 + a, o1 = x1 + b;
;                             *(u32x4*)(xb0 + off) = pack8(o0, o1);
;                             { u32x2 w8; w8.x = pack4_fp8(o0[0], o0[1], o0[2], o0[3]); w8.y = pack4_fp8(o1[0], o1[1], o1[2], o1[3]); *(u32x2*)((unsigned char*)zb + (size_t)row * (ZW * 2) + u.pn * 256 + bj * 128 + cl) = w8; }
;                             ss += (o0[0] * o0[0] + o0[1] * o0[1]) + (o0[2] * o0[2] + o0[3] * o0[3]) + (o1[0] * o1[0] + o1[1] * o1[1]) + (o1[2] * o1[2] + o1[3] * o1[3]); }
;                         ss += __shfl_xor(ss, 16); ss += __shfl_xor(ss, 32);
;                         if (fq == 0) ssq0[((size_t)u.pn * T_TOK + row) * 4 + wc] = ss; }
	v_cvt_pk_fp8_f32 v243, v82, v83 op_sel:[0,0,1]
	v_pk_mul_f32 v[248:249], v[84:85], v[84:85]
	v_pk_fma_f32 v[248:249], v[86:87], v[86:87], v[248:249]
	v_pk_fma_f32 v[248:249], v[80:81], v[80:81], v[248:249]
	v_pk_fma_f32 v[248:249], v[82:83], v[82:83], v[248:249]
	global_store_dwordx2 v185, v[242:243], s[44:45]
	v_add_f32_e32 v195, v248, v249
	v_pk_mul_f32 v[76:77], v[76:77], v[226:227] op_sel_hi:[1,0]
	v_pk_mul_f32 v[78:79], v[78:79], v[226:227] op_sel_hi:[1,0]
	v_pk_mul_f32 v[72:73], v[72:73], v[226:227] op_sel_hi:[1,0]
	v_pk_mul_f32 v[74:75], v[74:75], v[226:227] op_sel_hi:[1,0]
	v_pk_mul_f32 v[76:77], v[76:77], s[2:3] op_sel_hi:[1,0]
	v_pk_mul_f32 v[78:79], v[78:79], s[2:3] op_sel_hi:[1,0]
	v_pk_mul_f32 v[72:73], v[72:73], s[2:3] op_sel_hi:[1,0]
	v_pk_mul_f32 v[74:75], v[74:75], s[2:3] op_sel_hi:[1,0]
	v_exp_f32_e32 v76, v76
	v_exp_f32_e32 v77, v77
	v_exp_f32_e32 v78, v78
	v_exp_f32_e32 v79, v79
	v_exp_f32_e32 v72, v72
	v_exp_f32_e32 v73, v73
	v_exp_f32_e32 v74, v74
	v_exp_f32_e32 v75, v75
	v_pk_add_f32 v[76:77], v[76:77], s[74:75] op_sel_hi:[1,0]
	v_pk_add_f32 v[78:79], v[78:79], s[74:75] op_sel_hi:[1,0]
	v_pk_add_f32 v[72:73], v[72:73], s[74:75] op_sel_hi:[1,0]
	v_pk_add_f32 v[74:75], v[74:75], s[74:75] op_sel_hi:[1,0]
	v_rcp_f32_e32 v76, v76
	v_rcp_f32_e32 v77, v77
	v_rcp_f32_e32 v78, v78
	v_rcp_f32_e32 v79, v79
	v_rcp_f32_e32 v72, v72
	v_rcp_f32_e32 v73, v73
	v_rcp_f32_e32 v74, v74
	v_rcp_f32_e32 v75, v75
	v_lshlrev_b32_e32 v234, 16, v212
	v_and_b32_e32 v235, 0xffff0000, v212
	v_lshlrev_b32_e32 v236, 16, v213
	v_and_b32_e32 v237, 0xffff0000, v213
	v_lshlrev_b32_e32 v238, 16, v214
	v_and_b32_e32 v239, 0xffff0000, v214
	v_lshlrev_b32_e32 v240, 16, v215
	v_and_b32_e32 v241, 0xffff0000, v215
	v_lshlrev_b32_e32 v242, 16, v220
	v_and_b32_e32 v243, 0xffff0000, v220
	v_lshlrev_b32_e32 v244, 16, v221
	v_and_b32_e32 v245, 0xffff0000, v221
	v_lshlrev_b32_e32 v246, 16, v222
	v_and_b32_e32 v247, 0xffff0000, v222
	v_lshlrev_b32_e32 v248, 16, v223
	v_and_b32_e32 v249, 0xffff0000, v223
	v_pk_fma_f32 v[76:77], v[76:77], v[242:243], v[234:235]
	v_pk_fma_f32 v[78:79], v[78:79], v[244:245], v[236:237]
	v_pk_fma_f32 v[72:73], v[72:73], v[246:247], v[238:239]
	v_pk_fma_f32 v[74:75], v[74:75], v[248:249], v[240:241]
	v_cvt_pk_bf16_f32 v234, v76, v77
	v_cvt_pk_bf16_f32 v235, v78, v79
	v_cvt_pk_bf16_f32 v236, v72, v73
	v_cvt_pk_bf16_f32 v237, v74, v75
	global_store_dwordx4 v183, v[234:237], s[40:41] offset:256
	v_cvt_pk_fp8_f32 v242, v76, v77
	v_cvt_pk_fp8_f32 v243, v72, v73
	v_cvt_pk_fp8_f32 v242, v78, v79 op_sel:[0,0,1]
	v_cvt_pk_fp8_f32 v243, v74, v75 op_sel:[0,0,1]
	v_pk_mul_f32 v[248:249], v[76:77], v[76:77]
	v_pk_fma_f32 v[248:249], v[78:79], v[78:79], v[248:249]
	v_pk_fma_f32 v[248:249], v[72:73], v[72:73], v[248:249]
	v_pk_fma_f32 v[248:249], v[74:75], v[74:75], v[248:249]
	global_store_dwordx2 v185, v[242:243], s[44:45] offset:128
	v_add_f32_e32 v0, v248, v249
	v_add_f32_e32 v253, v195, v0
	s_waitcnt vmcnt(24)
	v_mov_b32_e32 v226, v254
	s_add_u32 s40, s12, 0x40000
	s_addc_u32 s41, s13, 0
	s_add_u32 s44, s10, 0xb0000
	s_addc_u32 s45, s11, 0
	v_pk_mul_f32 v[68:69], v[68:69], v[226:227] op_sel_hi:[1,0]
	v_pk_mul_f32 v[70:71], v[70:71], v[226:227] op_sel_hi:[1,0]
	v_pk_mul_f32 v[64:65], v[64:65], v[226:227] op_sel_hi:[1,0]
	v_pk_mul_f32 v[66:67], v[66:67], v[226:227] op_sel_hi:[1,0]
	v_pk_mul_f32 v[68:69], v[68:69], s[2:3] op_sel_hi:[1,0]
	v_pk_mul_f32 v[70:71], v[70:71], s[2:3] op_sel_hi:[1,0]
	v_pk_mul_f32 v[64:65], v[64:65], s[2:3] op_sel_hi:[1,0]
	v_pk_mul_f32 v[66:67], v[66:67], s[2:3] op_sel_hi:[1,0]
	v_exp_f32_e32 v68, v68
	v_exp_f32_e32 v69, v69
	v_exp_f32_e32 v70, v70
	v_exp_f32_e32 v71, v71
	v_exp_f32_e32 v64, v64
	v_exp_f32_e32 v65, v65
	v_exp_f32_e32 v66, v66
	v_exp_f32_e32 v67, v67
	v_pk_add_f32 v[68:69], v[68:69], s[74:75] op_sel_hi:[1,0]
	v_pk_add_f32 v[70:71], v[70:71], s[74:75] op_sel_hi:[1,0]
	v_pk_add_f32 v[64:65], v[64:65], s[74:75] op_sel_hi:[1,0]
	v_pk_add_f32 v[66:67], v[66:67], s[74:75] op_sel_hi:[1,0]
	v_rcp_f32_e32 v68, v68
	v_rcp_f32_e32 v69, v69
	v_rcp_f32_e32 v70, v70
	v_rcp_f32_e32 v71, v71
	v_rcp_f32_e32 v64, v64
	v_rcp_f32_e32 v65, v65
	v_rcp_f32_e32 v66, v66
	v_rcp_f32_e32 v67, v67
	v_lshlrev_b32_e32 v234, 16, v136
	v_and_b32_e32 v235, 0xffff0000, v136
	v_lshlrev_b32_e32 v236, 16, v137
	v_and_b32_e32 v237, 0xffff0000, v137
	v_lshlrev_b32_e32 v238, 16, v138
	v_and_b32_e32 v239, 0xffff0000, v138
	v_lshlrev_b32_e32 v240, 16, v139
	v_and_b32_e32 v241, 0xffff0000, v139
	v_lshlrev_b32_e32 v242, 16, v144
	v_and_b32_e32 v243, 0xffff0000, v144
	v_lshlrev_b32_e32 v244, 16, v145
	v_and_b32_e32 v245, 0xffff0000, v145
	v_lshlrev_b32_e32 v246, 16, v146
	v_and_b32_e32 v247, 0xffff0000, v146
	v_lshlrev_b32_e32 v248, 16, v147
	v_and_b32_e32 v249, 0xffff0000, v147
	v_pk_fma_f32 v[68:69], v[68:69], v[242:243], v[234:235]
	v_pk_fma_f32 v[70:71], v[70:71], v[244:245], v[236:237]
	v_pk_fma_f32 v[64:65], v[64:65], v[246:247], v[238:239]
	v_pk_fma_f32 v[66:67], v[66:67], v[248:249], v[240:241]
	v_cvt_pk_bf16_f32 v234, v68, v69
	v_cvt_pk_bf16_f32 v235, v70, v71
	v_cvt_pk_bf16_f32 v236, v64, v65
	v_cvt_pk_bf16_f32 v237, v66, v67
	global_store_dwordx4 v183, v[234:237], s[40:41]
	v_cvt_pk_fp8_f32 v242, v68, v69
	v_cvt_pk_fp8_f32 v243, v64, v65
	v_cvt_pk_fp8_f32 v242, v70, v71 op_sel:[0,0,1]
	v_cvt_pk_fp8_f32 v243, v66, v67 op_sel:[0,0,1]
	v_pk_mul_f32 v[248:249], v[68:69], v[68:69]
	v_pk_fma_f32 v[248:249], v[70:71], v[70:71], v[248:249]
	v_pk_fma_f32 v[248:249], v[64:65], v[64:65], v[248:249]
	v_pk_fma_f32 v[248:249], v[66:67], v[66:67], v[248:249]
	global_store_dwordx2 v185, v[242:243], s[44:45]
	v_add_f32_e32 v195, v248, v249
; __device__ __forceinline__ float sigmoidf_(float v) { return __builtin_amdgcn_rcpf(1.0f + __expf(-v)); }
; __device__ __forceinline__ u32x4 pack8(const f32x4 a, const f32x4 b) { u32x4 w; w.x = cvt_pk_bf16(a[0], a[1]); w.y = cvt_pk_bf16(a[2], a[3]); w.z = cvt_pk_bf16(b[0], b[1]); w.w = cvt_pk_bf16(b[2], b[3]); return w; }
; __device__ __forceinline__ void unpack8(const u32x4 w, f32x4& a, f32x4& b) { a[0] = bf_lo(w.x); a[1] = bf_hi(w.x); a[2] = bf_lo(w.y); a[3] = bf_hi(w.y); b[0] = bf_lo(w.z); b[1] = bf_hi(w.z); b[2] = bf_lo(w.w); b[3] = bf_hi(w.w); }
; __device__ __forceinline__ unsigned pack4_fp8(float a, float b, float c, float d) { unsigned w = 0u; w = __builtin_amdgcn_cvt_pk_fp8_f32(a, b, w, false); w = __builtin_amdgcn_cvt_pk_fp8_f32(c, d, w, true); return w; }
;     template <int KIND> __device__ __forceinline__ void run(f32x4 (&acc)[2][2][4][2], const Unit& u, int tid_in) const {
;     ...
;                     for (int ml = 0; ml < 2; ++ml) { const int m = mh * 2 + ml; int row = rbase + ai * 128 + m * 16; asm volatile("" : "+v"(row)); float ss = 0.f; const float r = rs[ai * 4 + m];
; #pragma unroll
;                         for (int bj = 0; bj < 2; ++bj) { const size_t off = (size_t)row * 1024 + u.pn * 256 + bj * 128 + cl; f32x4 a = acc[ai][bj][m][0], b = acc[ai][bj][m][1], p0, p1, x0, x1;
;                             unpack8(pv[ml][bj], p0, p1); unpack8(xv[ml][bj], x0, x1);
; #pragma unroll
;                             for (int j = 0; j < 4; ++j) { a[j] = sigmoidf_(a[j] * r) * p0[j]; b[j] = sigmoidf_(b[j] * r) * p1[j]; }
;                             const f32x4 o0 = x0 + a, o1 = x1 + b;
;                             *(u32x4*)(xb0 + off) = pack8(o0, o1);
;                             { u32x2 w8; w8.x = pack4_fp8(o0[0], o0[1], o0[2], o0[3]); w8.y = pack4_fp8(o1[0], o1[1], o1[2], o1[3]); *(u32x2*)((unsigned char*)zb + (size_t)row * (ZW * 2) + u.pn * 256 + bj * 128 + cl) = w8; }
;                             ss += (o0[0] * o0[0] + o0[1] * o0[1]) + (o0[2] * o0[2] + o0[3] * o0[3]) + (o1[0] * o1[0] + o1[1] * o1[1]) + (o1[2] * o1[2] + o1[3] * o1[3]); }
;                         ss += __shfl_xor(ss, 16); ss += __shfl_xor(ss, 32);
;                         if (fq == 0) ssq0[((size_t)u.pn * T_TOK + row) * 4 + wc] = ss; }
	v_pk_mul_f32 v[60:61], v[60:61], v[226:227] op_sel_hi:[1,0]
	v_pk_mul_f32 v[62:63], v[62:63], v[226:227] op_sel_hi:[1,0]
	v_pk_mul_f32 v[56:57], v[56:57], v[226:227] op_sel_hi:[1,0]
	v_pk_mul_f32 v[58:59], v[58:59], v[226:227] op_sel_hi:[1,0]
	v_pk_mul_f32 v[60:61], v[60:61], s[2:3] op_sel_hi:[1,0]
	v_pk_mul_f32 v[62:63], v[62:63], s[2:3] op_sel_hi:[1,0]
	v_pk_mul_f32 v[56:57], v[56:57], s[2:3] op_sel_hi:[1,0]
	v_pk_mul_f32 v[58:59], v[58:59], s[2:3] op_sel_hi:[1,0]
	v_exp_f32_e32 v60, v60
	v_exp_f32_e32 v61, v61
	v_exp_f32_e32 v62, v62
	v_exp_f32_e32 v63, v63
	v_exp_f32_e32 v56, v56
	v_exp_f32_e32 v57, v57
	v_exp_f32_e32 v58, v58
	v_exp_f32_e32 v59, v59
	v_pk_add_f32 v[60:61], v[60:61], s[74:75] op_sel_hi:[1,0]
	v_pk_add_f32 v[62:63], v[62:63], s[74:75] op_sel_hi:[1,0]
	v_pk_add_f32 v[56:57], v[56:57], s[74:75] op_sel_hi:[1,0]
	v_pk_add_f32 v[58:59], v[58:59], s[74:75] op_sel_hi:[1,0]
	v_rcp_f32_e32 v60, v60
	v_rcp_f32_e32 v61, v61
	v_rcp_f32_e32 v62, v62
	v_rcp_f32_e32 v63, v63
	v_rcp_f32_e32 v56, v56
	v_rcp_f32_e32 v57, v57
	v_rcp_f32_e32 v58, v58
	v_rcp_f32_e32 v59, v59
	v_lshlrev_b32_e32 v234, 16, v140
	v_and_b32_e32 v235, 0xffff0000, v140
	v_lshlrev_b32_e32 v236, 16, v141
	v_and_b32_e32 v237, 0xffff0000, v141
	v_lshlrev_b32_e32 v238, 16, v142
	v_and_b32_e32 v239, 0xffff0000, v142
	v_lshlrev_b32_e32 v240, 16, v143
	v_and_b32_e32 v241, 0xffff0000, v143
	v_lshlrev_b32_e32 v242, 16, v148
	v_and_b32_e32 v243, 0xffff0000, v148
	v_lshlrev_b32_e32 v244, 16, v149
	v_and_b32_e32 v245, 0xffff0000, v149
	v_lshlrev_b32_e32 v246, 16, v150
	v_and_b32_e32 v247, 0xffff0000, v150
	v_lshlrev_b32_e32 v248, 16, v151
	v_and_b32_e32 v249, 0xffff0000, v151
	v_pk_fma_f32 v[60:61], v[60:61], v[242:243], v[234:235]
	v_pk_fma_f32 v[62:63], v[62:63], v[244:245], v[236:237]
	v_pk_fma_f32 v[56:57], v[56:57], v[246:247], v[238:239]
	v_pk_fma_f32 v[58:59], v[58:59], v[248:249], v[240:241]
	v_cvt_pk_bf16_f32 v234, v60, v61
	v_cvt_pk_bf16_f32 v235, v62, v63
	v_cvt_pk_bf16_f32 v236, v56, v57
	v_cvt_pk_bf16_f32 v237, v58, v59
	global_store_dwordx4 v183, v[234:237], s[40:41] offset:256
	v_cvt_pk_fp8_f32 v242, v60, v61
	v_cvt_pk_fp8_f32 v243, v56, v57
	v_cvt_pk_fp8_f32 v242, v62, v63 op_sel:[0,0,1]
	v_cvt_pk_fp8_f32 v243, v58, v59 op_sel:[0,0,1]
	v_pk_mul_f32 v[248:249], v[60:61], v[60:61]
	v_pk_fma_f32 v[248:249], v[62:63], v[62:63], v[248:249]
	v_pk_fma_f32 v[248:249], v[56:57], v[56:57], v[248:249]
	v_pk_fma_f32 v[248:249], v[58:59], v[58:59], v[248:249]
	global_store_dwordx2 v185, v[242:243], s[44:45] offset:128
	v_add_f32_e32 v0, v248, v249
	v_add_f32_e32 v254, v195, v0
	s_waitcnt vmcnt(24)
	v_mov_b32_e32 v226, v255
	s_add_u32 s40, s12, 0x48000
	s_addc_u32 s41, s13, 0
	s_add_u32 s44, s10, 0xc6000
	s_addc_u32 s45, s11, 0
	v_pk_mul_f32 v[52:53], v[52:53], v[226:227] op_sel_hi:[1,0]
	v_pk_mul_f32 v[54:55], v[54:55], v[226:227] op_sel_hi:[1,0]
	v_pk_mul_f32 v[48:49], v[48:49], v[226:227] op_sel_hi:[1,0]
	v_pk_mul_f32 v[50:51], v[50:51], v[226:227] op_sel_hi:[1,0]
	v_pk_mul_f32 v[52:53], v[52:53], s[2:3] op_sel_hi:[1,0]
	v_pk_mul_f32 v[54:55], v[54:55], s[2:3] op_sel_hi:[1,0]
	v_pk_mul_f32 v[48:49], v[48:49], s[2:3] op_sel_hi:[1,0]
	v_pk_mul_f32 v[50:51], v[50:51], s[2:3] op_sel_hi:[1,0]
	v_exp_f32_e32 v52, v52
	v_exp_f32_e32 v53, v53
	v_exp_f32_e32 v54, v54
	v_exp_f32_e32 v55, v55
	v_exp_f32_e32 v48, v48
	v_exp_f32_e32 v49, v49
	v_exp_f32_e32 v50, v50
	v_exp_f32_e32 v51, v51
	v_pk_add_f32 v[52:53], v[52:53], s[74:75] op_sel_hi:[1,0]
	v_pk_add_f32 v[54:55], v[54:55], s[74:75] op_sel_hi:[1,0]
	v_pk_add_f32 v[48:49], v[48:49], s[74:75] op_sel_hi:[1,0]
	v_pk_add_f32 v[50:51], v[50:51], s[74:75] op_sel_hi:[1,0]
	v_rcp_f32_e32 v52, v52
	v_rcp_f32_e32 v53, v53
	v_rcp_f32_e32 v54, v54
	v_rcp_f32_e32 v55, v55
	v_rcp_f32_e32 v48, v48
	v_rcp_f32_e32 v49, v49
	v_rcp_f32_e32 v50, v50
	v_rcp_f32_e32 v51, v51
	v_lshlrev_b32_e32 v234, 16, v132
	v_and_b32_e32 v235, 0xffff0000, v132
	v_lshlrev_b32_e32 v236, 16, v133
	v_and_b32_e32 v237, 0xffff0000, v133
	v_lshlrev_b32_e32 v238, 16, v134
	v_and_b32_e32 v239, 0xffff0000, v134
	v_lshlrev_b32_e32 v240, 16, v135
	v_and_b32_e32 v241, 0xffff0000, v135
	v_lshlrev_b32_e32 v242, 16, v124
	v_and_b32_e32 v243, 0xffff0000, v124
	v_lshlrev_b32_e32 v244, 16, v125
	v_and_b32_e32 v245, 0xffff0000, v125
	v_lshlrev_b32_e32 v246, 16, v126
	v_and_b32_e32 v247, 0xffff0000, v126
	v_lshlrev_b32_e32 v248, 16, v127
	v_and_b32_e32 v249, 0xffff0000, v127
	v_pk_fma_f32 v[52:53], v[52:53], v[242:243], v[234:235]
	v_pk_fma_f32 v[54:55], v[54:55], v[244:245], v[236:237]
	v_pk_fma_f32 v[48:49], v[48:49], v[246:247], v[238:239]
	v_pk_fma_f32 v[50:51], v[50:51], v[248:249], v[240:241]
	v_cvt_pk_bf16_f32 v234, v52, v53
	v_cvt_pk_bf16_f32 v235, v54, v55
	v_cvt_pk_bf16_f32 v236, v48, v49
	v_cvt_pk_bf16_f32 v237, v50, v51
	global_store_dwordx4 v183, v[234:237], s[40:41]
	v_cvt_pk_fp8_f32 v242, v52, v53
	v_cvt_pk_fp8_f32 v243, v48, v49
	v_cvt_pk_fp8_f32 v242, v54, v55 op_sel:[0,0,1]
	v_cvt_pk_fp8_f32 v243, v50, v51 op_sel:[0,0,1]
	v_pk_mul_f32 v[248:249], v[52:53], v[52:53]
	v_pk_fma_f32 v[248:249], v[54:55], v[54:55], v[248:249]
	v_pk_fma_f32 v[248:249], v[48:49], v[48:49], v[248:249]
	v_pk_fma_f32 v[248:249], v[50:51], v[50:51], v[248:249]
	global_store_dwordx2 v185, v[242:243], s[44:45]
	v_add_f32_e32 v195, v248, v249
	v_pk_mul_f32 v[44:45], v[44:45], v[226:227] op_sel_hi:[1,0]
	v_pk_mul_f32 v[46:47], v[46:47], v[226:227] op_sel_hi:[1,0]
	v_pk_mul_f32 v[40:41], v[40:41], v[226:227] op_sel_hi:[1,0]
	v_pk_mul_f32 v[42:43], v[42:43], v[226:227] op_sel_hi:[1,0]
	v_pk_mul_f32 v[44:45], v[44:45], s[2:3] op_sel_hi:[1,0]
	v_pk_mul_f32 v[46:47], v[46:47], s[2:3] op_sel_hi:[1,0]
; __device__ __forceinline__ float sigmoidf_(float v) { return __builtin_amdgcn_rcpf(1.0f + __expf(-v)); }
; __device__ __forceinline__ u32x4 pack8(const f32x4 a, const f32x4 b) { u32x4 w; w.x = cvt_pk_bf16(a[0], a[1]); w.y = cvt_pk_bf16(a[2], a[3]); w.z = cvt_pk_bf16(b[0], b[1]); w.w = cvt_pk_bf16(b[2], b[3]); return w; }
; __device__ __forceinline__ void unpack8(const u32x4 w, f32x4& a, f32x4& b) { a[0] = bf_lo(w.x); a[1] = bf_hi(w.x); a[2] = bf_lo(w.y); a[3] = bf_hi(w.y); b[0] = bf_lo(w.z); b[1] = bf_hi(w.z); b[2] = bf_lo(w.w); b[3] = bf_hi(w.w); }
; __device__ __forceinline__ unsigned pack4_fp8(float a, float b, float c, float d) { unsigned w = 0u; w = __builtin_amdgcn_cvt_pk_fp8_f32(a, b, w, false); w = __builtin_amdgcn_cvt_pk_fp8_f32(c, d, w, true); return w; }
;     template <int KIND> __device__ __forceinline__ void run(f32x4 (&acc)[2][2][4][2], const Unit& u, int tid_in) const {
;     ...
;                     for (int ml = 0; ml < 2; ++ml) { const int m = mh * 2 + ml; int row = rbase + ai * 128 + m * 16; asm volatile("" : "+v"(row)); float ss = 0.f; const float r = rs[ai * 4 + m];
; #pragma unroll
;                         for (int bj = 0; bj < 2; ++bj) { const size_t off = (size_t)row * 1024 + u.pn * 256 + bj * 128 + cl; f32x4 a = acc[ai][bj][m][0], b = acc[ai][bj][m][1], p0, p1, x0, x1;
;                             unpack8(pv[ml][bj], p0, p1); unpack8(xv[ml][bj], x0, x1);
; #pragma unroll
;                             for (int j = 0; j < 4; ++j) { a[j] = sigmoidf_(a[j] * r) * p0[j]; b[j] = sigmoidf_(b[j] * r) * p1[j]; }
;                             const f32x4 o0 = x0 + a, o1 = x1 + b;
;                             *(u32x4*)(xb0 + off) = pack8(o0, o1);
;                             { u32x2 w8; w8.x = pack4_fp8(o0[0], o0[1], o0[2], o0[3]); w8.y = pack4_fp8(o1[0], o1[1], o1[2], o1[3]); *(u32x2*)((unsigned char*)zb + (size_t)row * (ZW * 2) + u.pn * 256 + bj * 128 + cl) = w8; }
;                             ss += (o0[0] * o0[0] + o0[1] * o0[1]) + (o0[2] * o0[2] + o0[3] * o0[3]) + (o1[0] * o1[0] + o1[1] * o1[1]) + (o1[2] * o1[2] + o1[3] * o1[3]); }
;                         ss += __shfl_xor(ss, 16); ss += __shfl_xor(ss, 32);
;                         if (fq == 0) ssq0[((size_t)u.pn * T_TOK + row) * 4 + wc] = ss; }
	v_pk_mul_f32 v[40:41], v[40:41], s[2:3] op_sel_hi:[1,0]
	v_pk_mul_f32 v[42:43], v[42:43], s[2:3] op_sel_hi:[1,0]
	v_exp_f32_e32 v44, v44
	v_exp_f32_e32 v45, v45
	v_exp_f32_e32 v46, v46
	v_exp_f32_e32 v47, v47
	v_exp_f32_e32 v40, v40
	v_exp_f32_e32 v41, v41
	v_exp_f32_e32 v42, v42
	v_exp_f32_e32 v43, v43
	v_pk_add_f32 v[44:45], v[44:45], s[74:75] op_sel_hi:[1,0]
	v_pk_add_f32 v[46:47], v[46:47], s[74:75] op_sel_hi:[1,0]
	v_pk_add_f32 v[40:41], v[40:41], s[74:75] op_sel_hi:[1,0]
	v_pk_add_f32 v[42:43], v[42:43], s[74:75] op_sel_hi:[1,0]
	v_rcp_f32_e32 v44, v44
	v_rcp_f32_e32 v45, v45
	v_rcp_f32_e32 v46, v46
	v_rcp_f32_e32 v47, v47
	v_rcp_f32_e32 v40, v40
	v_rcp_f32_e32 v41, v41
	v_rcp_f32_e32 v42, v42
	v_rcp_f32_e32 v43, v43
	v_lshlrev_b32_e32 v234, 16, v128
	v_and_b32_e32 v235, 0xffff0000, v128
	v_lshlrev_b32_e32 v236, 16, v129
	v_and_b32_e32 v237, 0xffff0000, v129
	v_lshlrev_b32_e32 v238, 16, v130
	v_and_b32_e32 v239, 0xffff0000, v130
	v_lshlrev_b32_e32 v240, 16, v131
	v_and_b32_e32 v241, 0xffff0000, v131
	v_lshlrev_b32_e32 v242, 16, v120
	v_and_b32_e32 v243, 0xffff0000, v120
	v_lshlrev_b32_e32 v244, 16, v121
	v_and_b32_e32 v245, 0xffff0000, v121
	v_lshlrev_b32_e32 v246, 16, v122
	v_and_b32_e32 v247, 0xffff0000, v122
	v_lshlrev_b32_e32 v248, 16, v123
	v_and_b32_e32 v249, 0xffff0000, v123
	v_pk_fma_f32 v[44:45], v[44:45], v[242:243], v[234:235]
	v_pk_fma_f32 v[46:47], v[46:47], v[244:245], v[236:237]
	v_pk_fma_f32 v[40:41], v[40:41], v[246:247], v[238:239]
	v_pk_fma_f32 v[42:43], v[42:43], v[248:249], v[240:241]
	v_cvt_pk_bf16_f32 v234, v44, v45
	v_cvt_pk_bf16_f32 v235, v46, v47
	v_cvt_pk_bf16_f32 v236, v40, v41
	v_cvt_pk_bf16_f32 v237, v42, v43
	global_store_dwordx4 v183, v[234:237], s[40:41] offset:256
	v_cvt_pk_fp8_f32 v242, v44, v45
	v_cvt_pk_fp8_f32 v243, v40, v41
	v_cvt_pk_fp8_f32 v242, v46, v47 op_sel:[0,0,1]
	v_cvt_pk_fp8_f32 v243, v42, v43 op_sel:[0,0,1]
	v_pk_mul_f32 v[248:249], v[44:45], v[44:45]
	v_pk_fma_f32 v[248:249], v[46:47], v[46:47], v[248:249]
	v_pk_fma_f32 v[248:249], v[40:41], v[40:41], v[248:249]
	v_pk_fma_f32 v[248:249], v[42:43], v[42:43], v[248:249]
	global_store_dwordx2 v185, v[242:243], s[44:45] offset:128
	v_add_f32_e32 v0, v248, v249
	v_add_f32_e32 v255, v195, v0
	s_waitcnt vmcnt(20)
	v_mov_b32_e32 v226, v224
	s_add_u32 s40, s12, 0x50000
	s_addc_u32 s41, s13, 0
	s_add_u32 s44, s10, 0xdc000
	s_addc_u32 s45, s11, 0
	v_pk_mul_f32 v[36:37], v[36:37], v[226:227] op_sel_hi:[1,0]
	v_pk_mul_f32 v[38:39], v[38:39], v[226:227] op_sel_hi:[1,0]
	v_pk_mul_f32 v[32:33], v[32:33], v[226:227] op_sel_hi:[1,0]
	v_pk_mul_f32 v[34:35], v[34:35], v[226:227] op_sel_hi:[1,0]
	v_pk_mul_f32 v[36:37], v[36:37], s[2:3] op_sel_hi:[1,0]
	v_pk_mul_f32 v[38:39], v[38:39], s[2:3] op_sel_hi:[1,0]
	v_pk_mul_f32 v[32:33], v[32:33], s[2:3] op_sel_hi:[1,0]
	v_pk_mul_f32 v[34:35], v[34:35], s[2:3] op_sel_hi:[1,0]
	v_exp_f32_e32 v36, v36
	v_exp_f32_e32 v37, v37
	v_exp_f32_e32 v38, v38
	v_exp_f32_e32 v39, v39
	v_exp_f32_e32 v32, v32
	v_exp_f32_e32 v33, v33
	v_exp_f32_e32 v34, v34
	v_exp_f32_e32 v35, v35
	v_pk_add_f32 v[36:37], v[36:37], s[74:75] op_sel_hi:[1,0]
	v_pk_add_f32 v[38:39], v[38:39], s[74:75] op_sel_hi:[1,0]
	v_pk_add_f32 v[32:33], v[32:33], s[74:75] op_sel_hi:[1,0]
	v_pk_add_f32 v[34:35], v[34:35], s[74:75] op_sel_hi:[1,0]
	v_rcp_f32_e32 v36, v36
	v_rcp_f32_e32 v37, v37
	v_rcp_f32_e32 v38, v38
	v_rcp_f32_e32 v39, v39
	v_rcp_f32_e32 v32, v32
	v_rcp_f32_e32 v33, v33
	v_rcp_f32_e32 v34, v34
	v_rcp_f32_e32 v35, v35
	v_lshlrev_b32_e32 v234, 16, v152
	v_and_b32_e32 v235, 0xffff0000, v152
	v_lshlrev_b32_e32 v236, 16, v153
	v_and_b32_e32 v237, 0xffff0000, v153
	v_lshlrev_b32_e32 v238, 16, v154
	v_and_b32_e32 v239, 0xffff0000, v154
	v_lshlrev_b32_e32 v240, 16, v155
	v_and_b32_e32 v241, 0xffff0000, v155
	v_lshlrev_b32_e32 v242, 16, v164
	v_and_b32_e32 v243, 0xffff0000, v164
	v_lshlrev_b32_e32 v244, 16, v165
	v_and_b32_e32 v245, 0xffff0000, v165
	v_lshlrev_b32_e32 v246, 16, v166
	v_and_b32_e32 v247, 0xffff0000, v166
	v_lshlrev_b32_e32 v248, 16, v167
	v_and_b32_e32 v249, 0xffff0000, v167
	v_pk_fma_f32 v[36:37], v[36:37], v[242:243], v[234:235]
	v_pk_fma_f32 v[38:39], v[38:39], v[244:245], v[236:237]
	v_pk_fma_f32 v[32:33], v[32:33], v[246:247], v[238:239]
	v_pk_fma_f32 v[34:35], v[34:35], v[248:249], v[240:241]
	v_cvt_pk_bf16_f32 v234, v36, v37
	v_cvt_pk_bf16_f32 v235, v38, v39
	v_cvt_pk_bf16_f32 v236, v32, v33
	v_cvt_pk_bf16_f32 v237, v34, v35
	global_store_dwordx4 v183, v[234:237], s[40:41]
	v_cvt_pk_fp8_f32 v242, v36, v37
	v_cvt_pk_fp8_f32 v243, v32, v33
	v_cvt_pk_fp8_f32 v242, v38, v39 op_sel:[0,0,1]
	v_cvt_pk_fp8_f32 v243, v34, v35 op_sel:[0,0,1]
	v_pk_mul_f32 v[248:249], v[36:37], v[36:37]
	v_pk_fma_f32 v[248:249], v[38:39], v[38:39], v[248:249]
	v_pk_fma_f32 v[248:249], v[32:33], v[32:33], v[248:249]
	v_pk_fma_f32 v[248:249], v[34:35], v[34:35], v[248:249]
	global_store_dwordx2 v185, v[242:243], s[44:45]
	v_add_f32_e32 v195, v248, v249
	v_pk_mul_f32 v[28:29], v[28:29], v[226:227] op_sel_hi:[1,0]
	v_pk_mul_f32 v[30:31], v[30:31], v[226:227] op_sel_hi:[1,0]
	v_pk_mul_f32 v[24:25], v[24:25], v[226:227] op_sel_hi:[1,0]
	v_pk_mul_f32 v[26:27], v[26:27], v[226:227] op_sel_hi:[1,0]
	v_pk_mul_f32 v[28:29], v[28:29], s[2:3] op_sel_hi:[1,0]
	v_pk_mul_f32 v[30:31], v[30:31], s[2:3] op_sel_hi:[1,0]
	v_pk_mul_f32 v[24:25], v[24:25], s[2:3] op_sel_hi:[1,0]
	v_pk_mul_f32 v[26:27], v[26:27], s[2:3] op_sel_hi:[1,0]
	v_exp_f32_e32 v28, v28
	v_exp_f32_e32 v29, v29
	v_exp_f32_e32 v30, v30
	v_exp_f32_e32 v31, v31
	v_exp_f32_e32 v24, v24
	v_exp_f32_e32 v25, v25
	v_exp_f32_e32 v26, v26
	v_exp_f32_e32 v27, v27
	v_pk_add_f32 v[28:29], v[28:29], s[74:75] op_sel_hi:[1,0]
; __device__ __forceinline__ float sigmoidf_(float v) { return __builtin_amdgcn_rcpf(1.0f + __expf(-v)); }
; __device__ __forceinline__ u32x4 pack8(const f32x4 a, const f32x4 b) { u32x4 w; w.x = cvt_pk_bf16(a[0], a[1]); w.y = cvt_pk_bf16(a[2], a[3]); w.z = cvt_pk_bf16(b[0], b[1]); w.w = cvt_pk_bf16(b[2], b[3]); return w; }
; __device__ __forceinline__ void unpack8(const u32x4 w, f32x4& a, f32x4& b) { a[0] = bf_lo(w.x); a[1] = bf_hi(w.x); a[2] = bf_lo(w.y); a[3] = bf_hi(w.y); b[0] = bf_lo(w.z); b[1] = bf_hi(w.z); b[2] = bf_lo(w.w); b[3] = bf_hi(w.w); }
; __device__ __forceinline__ unsigned pack4_fp8(float a, float b, float c, float d) { unsigned w = 0u; w = __builtin_amdgcn_cvt_pk_fp8_f32(a, b, w, false); w = __builtin_amdgcn_cvt_pk_fp8_f32(c, d, w, true); return w; }
;     template <int KIND> __device__ __forceinline__ void run(f32x4 (&acc)[2][2][4][2], const Unit& u, int tid_in) const {
;     ...
;                     for (int ml = 0; ml < 2; ++ml) { const int m = mh * 2 + ml; int row = rbase + ai * 128 + m * 16; asm volatile("" : "+v"(row)); float ss = 0.f; const float r = rs[ai * 4 + m];
; #pragma unroll
;                         for (int bj = 0; bj < 2; ++bj) { const size_t off = (size_t)row * 1024 + u.pn * 256 + bj * 128 + cl; f32x4 a = acc[ai][bj][m][0], b = acc[ai][bj][m][1], p0, p1, x0, x1;
;                             unpack8(pv[ml][bj], p0, p1); unpack8(xv[ml][bj], x0, x1);
; #pragma unroll
;                             for (int j = 0; j < 4; ++j) { a[j] = sigmoidf_(a[j] * r) * p0[j]; b[j] = sigmoidf_(b[j] * r) * p1[j]; }
;                             const f32x4 o0 = x0 + a, o1 = x1 + b;
;                             *(u32x4*)(xb0 + off) = pack8(o0, o1);
;                             { u32x2 w8; w8.x = pack4_fp8(o0[0], o0[1], o0[2], o0[3]); w8.y = pack4_fp8(o1[0], o1[1], o1[2], o1[3]); *(u32x2*)((unsigned char*)zb + (size_t)row * (ZW * 2) + u.pn * 256 + bj * 128 + cl) = w8; }
;                             ss += (o0[0] * o0[0] + o0[1] * o0[1]) + (o0[2] * o0[2] + o0[3] * o0[3]) + (o1[0] * o1[0] + o1[1] * o1[1]) + (o1[2] * o1[2] + o1[3] * o1[3]); }
;                         ss += __shfl_xor(ss, 16); ss += __shfl_xor(ss, 32);
;                         if (fq == 0) ssq0[((size_t)u.pn * T_TOK + row) * 4 + wc] = ss; }
	v_pk_add_f32 v[30:31], v[30:31], s[74:75] op_sel_hi:[1,0]
	v_pk_add_f32 v[24:25], v[24:25], s[74:75] op_sel_hi:[1,0]
	v_pk_add_f32 v[26:27], v[26:27], s[74:75] op_sel_hi:[1,0]
	v_rcp_f32_e32 v28, v28
	v_rcp_f32_e32 v29, v29
	v_rcp_f32_e32 v30, v30
	v_rcp_f32_e32 v31, v31
	v_rcp_f32_e32 v24, v24
	v_rcp_f32_e32 v25, v25
	v_rcp_f32_e32 v26, v26
	v_rcp_f32_e32 v27, v27
	v_lshlrev_b32_e32 v234, 16, v160
	v_and_b32_e32 v235, 0xffff0000, v160
	v_lshlrev_b32_e32 v236, 16, v161
	v_and_b32_e32 v237, 0xffff0000, v161
	v_lshlrev_b32_e32 v238, 16, v162
	v_and_b32_e32 v239, 0xffff0000, v162
	v_lshlrev_b32_e32 v240, 16, v163
	v_and_b32_e32 v241, 0xffff0000, v163
	v_lshlrev_b32_e32 v242, 16, v172
	v_and_b32_e32 v243, 0xffff0000, v172
	v_lshlrev_b32_e32 v244, 16, v173
	v_and_b32_e32 v245, 0xffff0000, v173
	v_lshlrev_b32_e32 v246, 16, v174
	v_and_b32_e32 v247, 0xffff0000, v174
	v_lshlrev_b32_e32 v248, 16, v175
	v_and_b32_e32 v249, 0xffff0000, v175
	v_pk_fma_f32 v[28:29], v[28:29], v[242:243], v[234:235]
	v_pk_fma_f32 v[30:31], v[30:31], v[244:245], v[236:237]
	v_pk_fma_f32 v[24:25], v[24:25], v[246:247], v[238:239]
	v_pk_fma_f32 v[26:27], v[26:27], v[248:249], v[240:241]
	v_cvt_pk_bf16_f32 v234, v28, v29
	v_cvt_pk_bf16_f32 v235, v30, v31
	v_cvt_pk_bf16_f32 v236, v24, v25
	v_cvt_pk_bf16_f32 v237, v26, v27
	global_store_dwordx4 v183, v[234:237], s[40:41] offset:256
	v_cvt_pk_fp8_f32 v242, v28, v29
	v_cvt_pk_fp8_f32 v243, v24, v25
	v_cvt_pk_fp8_f32 v242, v30, v31 op_sel:[0,0,1]
	v_cvt_pk_fp8_f32 v243, v26, v27 op_sel:[0,0,1]
	v_pk_mul_f32 v[248:249], v[28:29], v[28:29]
	v_pk_fma_f32 v[248:249], v[30:31], v[30:31], v[248:249]
	v_pk_fma_f32 v[248:249], v[24:25], v[24:25], v[248:249]
	v_pk_fma_f32 v[248:249], v[26:27], v[26:27], v[248:249]
	global_store_dwordx2 v185, v[242:243], s[44:45] offset:128
	v_add_f32_e32 v0, v248, v249
	v_add_f32_e32 v224, v195, v0
	s_waitcnt vmcnt(20)
	v_mov_b32_e32 v226, v225
	s_add_u32 s40, s12, 0x58000
	s_addc_u32 s41, s13, 0
	s_add_u32 s44, s10, 0xf2000
	s_addc_u32 s45, s11, 0
	v_pk_mul_f32 v[20:21], v[20:21], v[226:227] op_sel_hi:[1,0]
	v_pk_mul_f32 v[22:23], v[22:23], v[226:227] op_sel_hi:[1,0]
	v_pk_mul_f32 v[16:17], v[16:17], v[226:227] op_sel_hi:[1,0]
	v_pk_mul_f32 v[18:19], v[18:19], v[226:227] op_sel_hi:[1,0]
	v_pk_mul_f32 v[20:21], v[20:21], s[2:3] op_sel_hi:[1,0]
	v_pk_mul_f32 v[22:23], v[22:23], s[2:3] op_sel_hi:[1,0]
	v_pk_mul_f32 v[16:17], v[16:17], s[2:3] op_sel_hi:[1,0]
	v_pk_mul_f32 v[18:19], v[18:19], s[2:3] op_sel_hi:[1,0]
	v_exp_f32_e32 v20, v20
	v_exp_f32_e32 v21, v21
	v_exp_f32_e32 v22, v22
	v_exp_f32_e32 v23, v23
	v_exp_f32_e32 v16, v16
	v_exp_f32_e32 v17, v17
	v_exp_f32_e32 v18, v18
	v_exp_f32_e32 v19, v19
	v_pk_add_f32 v[20:21], v[20:21], s[74:75] op_sel_hi:[1,0]
	v_pk_add_f32 v[22:23], v[22:23], s[74:75] op_sel_hi:[1,0]
	v_pk_add_f32 v[16:17], v[16:17], s[74:75] op_sel_hi:[1,0]
	v_pk_add_f32 v[18:19], v[18:19], s[74:75] op_sel_hi:[1,0]
	v_rcp_f32_e32 v20, v20
	v_rcp_f32_e32 v21, v21
	v_rcp_f32_e32 v22, v22
	v_rcp_f32_e32 v23, v23
	v_rcp_f32_e32 v16, v16
	v_rcp_f32_e32 v17, v17
	v_rcp_f32_e32 v18, v18
	v_rcp_f32_e32 v19, v19
	v_lshlrev_b32_e32 v234, 16, v116
	v_and_b32_e32 v235, 0xffff0000, v116
	v_lshlrev_b32_e32 v236, 16, v117
	v_and_b32_e32 v237, 0xffff0000, v117
	v_lshlrev_b32_e32 v238, 16, v118
	v_and_b32_e32 v239, 0xffff0000, v118
	v_lshlrev_b32_e32 v240, 16, v119
	v_and_b32_e32 v241, 0xffff0000, v119
	v_lshlrev_b32_e32 v242, 16, v108
	v_and_b32_e32 v243, 0xffff0000, v108
	v_lshlrev_b32_e32 v244, 16, v109
	v_and_b32_e32 v245, 0xffff0000, v109
	v_lshlrev_b32_e32 v246, 16, v110
	v_and_b32_e32 v247, 0xffff0000, v110
	v_lshlrev_b32_e32 v248, 16, v111
	v_and_b32_e32 v249, 0xffff0000, v111
	v_pk_fma_f32 v[20:21], v[20:21], v[242:243], v[234:235]
	v_pk_fma_f32 v[22:23], v[22:23], v[244:245], v[236:237]
	v_pk_fma_f32 v[16:17], v[16:17], v[246:247], v[238:239]
	v_pk_fma_f32 v[18:19], v[18:19], v[248:249], v[240:241]
	v_cvt_pk_bf16_f32 v234, v20, v21
	v_cvt_pk_bf16_f32 v235, v22, v23
	v_cvt_pk_bf16_f32 v236, v16, v17
	v_cvt_pk_bf16_f32 v237, v18, v19
	global_store_dwordx4 v183, v[234:237], s[40:41]
	v_cvt_pk_fp8_f32 v242, v20, v21
	v_cvt_pk_fp8_f32 v243, v16, v17
	v_cvt_pk_fp8_f32 v242, v22, v23 op_sel:[0,0,1]
	v_cvt_pk_fp8_f32 v243, v18, v19 op_sel:[0,0,1]
	v_pk_mul_f32 v[248:249], v[20:21], v[20:21]
	v_pk_fma_f32 v[248:249], v[22:23], v[22:23], v[248:249]
	v_pk_fma_f32 v[248:249], v[16:17], v[16:17], v[248:249]
	v_pk_fma_f32 v[248:249], v[18:19], v[18:19], v[248:249]
	global_store_dwordx2 v185, v[242:243], s[44:45]
	v_add_f32_e32 v195, v248, v249
; __device__ __forceinline__ float sigmoidf_(float v) { return __builtin_amdgcn_rcpf(1.0f + __expf(-v)); }
; __device__ __forceinline__ u32x4 pack8(const f32x4 a, const f32x4 b) { u32x4 w; w.x = cvt_pk_bf16(a[0], a[1]); w.y = cvt_pk_bf16(a[2], a[3]); w.z = cvt_pk_bf16(b[0], b[1]); w.w = cvt_pk_bf16(b[2], b[3]); return w; }
; __device__ __forceinline__ void unpack8(const u32x4 w, f32x4& a, f32x4& b) { a[0] = bf_lo(w.x); a[1] = bf_hi(w.x); a[2] = bf_lo(w.y); a[3] = bf_hi(w.y); b[0] = bf_lo(w.z); b[1] = bf_hi(w.z); b[2] = bf_lo(w.w); b[3] = bf_hi(w.w); }
; __device__ __forceinline__ unsigned pack4_fp8(float a, float b, float c, float d) { unsigned w = 0u; w = __builtin_amdgcn_cvt_pk_fp8_f32(a, b, w, false); w = __builtin_amdgcn_cvt_pk_fp8_f32(c, d, w, true); return w; }
; #define MEMFENCE asm volatile("" ::: "memory")
;     template <int KIND> __device__ __forceinline__ void run(f32x4 (&acc)[2][2][4][2], const Unit& u, int tid_in) const {
;     ...
;                     for (int ml = 0; ml < 2; ++ml) { const int m = mh * 2 + ml; int row = rbase + ai * 128 + m * 16; asm volatile("" : "+v"(row)); float ss = 0.f; const float r = rs[ai * 4 + m];
; #pragma unroll
;                         for (int bj = 0; bj < 2; ++bj) { const size_t off = (size_t)row * 1024 + u.pn * 256 + bj * 128 + cl; f32x4 a = acc[ai][bj][m][0], b = acc[ai][bj][m][1], p0, p1, x0, x1;
;                             unpack8(pv[ml][bj], p0, p1); unpack8(xv[ml][bj], x0, x1);
; #pragma unroll
;                             for (int j = 0; j < 4; ++j) { a[j] = sigmoidf_(a[j] * r) * p0[j]; b[j] = sigmoidf_(b[j] * r) * p1[j]; }
;                             const f32x4 o0 = x0 + a, o1 = x1 + b;
;                             *(u32x4*)(xb0 + off) = pack8(o0, o1);
;                             { u32x2 w8; w8.x = pack4_fp8(o0[0], o0[1], o0[2], o0[3]); w8.y = pack4_fp8(o1[0], o1[1], o1[2], o1[3]); *(u32x2*)((unsigned char*)zb + (size_t)row * (ZW * 2) + u.pn * 256 + bj * 128 + cl) = w8; }
;                             ss += (o0[0] * o0[0] + o0[1] * o0[1]) + (o0[2] * o0[2] + o0[3] * o0[3]) + (o1[0] * o1[0] + o1[1] * o1[1]) + (o1[2] * o1[2] + o1[3] * o1[3]); }
;                         ss += __shfl_xor(ss, 16); ss += __shfl_xor(ss, 32);
;                         if (fq == 0) ssq0[((size_t)u.pn * T_TOK + row) * 4 + wc] = ss; }
;                     MEMFENCE; }
	v_pk_mul_f32 v[12:13], v[12:13], v[226:227] op_sel_hi:[1,0]
	v_pk_mul_f32 v[14:15], v[14:15], v[226:227] op_sel_hi:[1,0]
	v_pk_mul_f32 v[8:9], v[8:9], v[226:227] op_sel_hi:[1,0]
	v_pk_mul_f32 v[10:11], v[10:11], v[226:227] op_sel_hi:[1,0]
	v_pk_mul_f32 v[12:13], v[12:13], s[2:3] op_sel_hi:[1,0]
	v_pk_mul_f32 v[14:15], v[14:15], s[2:3] op_sel_hi:[1,0]
	v_pk_mul_f32 v[8:9], v[8:9], s[2:3] op_sel_hi:[1,0]
	v_pk_mul_f32 v[10:11], v[10:11], s[2:3] op_sel_hi:[1,0]
	v_exp_f32_e32 v12, v12
	v_exp_f32_e32 v13, v13
	v_exp_f32_e32 v14, v14
	v_exp_f32_e32 v15, v15
	v_exp_f32_e32 v8, v8
	v_exp_f32_e32 v9, v9
	v_exp_f32_e32 v10, v10
	v_exp_f32_e32 v11, v11
	v_pk_add_f32 v[12:13], v[12:13], s[74:75] op_sel_hi:[1,0]
	v_pk_add_f32 v[14:15], v[14:15], s[74:75] op_sel_hi:[1,0]
	v_pk_add_f32 v[8:9], v[8:9], s[74:75] op_sel_hi:[1,0]
	v_pk_add_f32 v[10:11], v[10:11], s[74:75] op_sel_hi:[1,0]
	v_rcp_f32_e32 v12, v12
	v_rcp_f32_e32 v13, v13
	v_rcp_f32_e32 v14, v14
	v_rcp_f32_e32 v15, v15
	v_rcp_f32_e32 v8, v8
	v_rcp_f32_e32 v9, v9
	v_rcp_f32_e32 v10, v10
	v_rcp_f32_e32 v11, v11
	v_lshlrev_b32_e32 v234, 16, v112
	v_and_b32_e32 v235, 0xffff0000, v112
	v_lshlrev_b32_e32 v236, 16, v113
	v_and_b32_e32 v237, 0xffff0000, v113
	v_lshlrev_b32_e32 v238, 16, v114
	v_and_b32_e32 v239, 0xffff0000, v114
	v_lshlrev_b32_e32 v240, 16, v115
	v_and_b32_e32 v241, 0xffff0000, v115
	v_lshlrev_b32_e32 v242, 16, v104
	v_and_b32_e32 v243, 0xffff0000, v104
	v_lshlrev_b32_e32 v244, 16, v105
	v_and_b32_e32 v245, 0xffff0000, v105
	v_lshlrev_b32_e32 v246, 16, v106
	v_and_b32_e32 v247, 0xffff0000, v106
	v_lshlrev_b32_e32 v248, 16, v107
	v_and_b32_e32 v249, 0xffff0000, v107
	v_pk_fma_f32 v[12:13], v[12:13], v[242:243], v[234:235]
	v_pk_fma_f32 v[14:15], v[14:15], v[244:245], v[236:237]
	v_pk_fma_f32 v[8:9], v[8:9], v[246:247], v[238:239]
	v_pk_fma_f32 v[10:11], v[10:11], v[248:249], v[240:241]
	v_cvt_pk_bf16_f32 v234, v12, v13
	v_cvt_pk_bf16_f32 v235, v14, v15
	v_cvt_pk_bf16_f32 v236, v8, v9
	v_cvt_pk_bf16_f32 v237, v10, v11
	global_store_dwordx4 v183, v[234:237], s[40:41] offset:256
	v_cvt_pk_fp8_f32 v242, v12, v13
	v_cvt_pk_fp8_f32 v243, v8, v9
	v_cvt_pk_fp8_f32 v242, v14, v15 op_sel:[0,0,1]
	v_cvt_pk_fp8_f32 v243, v10, v11 op_sel:[0,0,1]
	v_pk_mul_f32 v[248:249], v[12:13], v[12:13]
	v_pk_fma_f32 v[248:249], v[14:15], v[14:15], v[248:249]
	v_pk_fma_f32 v[248:249], v[8:9], v[8:9], v[248:249]
	v_pk_fma_f32 v[248:249], v[10:11], v[10:11], v[248:249]
	global_store_dwordx2 v185, v[242:243], s[44:45] offset:128
	v_add_f32_e32 v0, v248, v249
	v_add_f32_e32 v225, v195, v0
	v_xor_b32_e32 v234, 16, v190
	v_xor_b32_e32 v235, 32, v190
	v_lshlrev_b32_e32 v234, 2, v234
	v_lshlrev_b32_e32 v235, 2, v235
	ds_bpermute_b32 v236, v234, v250
	ds_bpermute_b32 v237, v234, v251
	ds_bpermute_b32 v238, v234, v252
	ds_bpermute_b32 v239, v234, v253
	ds_bpermute_b32 v240, v234, v254
	ds_bpermute_b32 v241, v234, v255
	ds_bpermute_b32 v242, v234, v224
	ds_bpermute_b32 v243, v234, v225
	s_waitcnt lgkmcnt(0)
	v_add_f32_e32 v250, v250, v236
	v_add_f32_e32 v251, v251, v237
	v_add_f32_e32 v252, v252, v238
	v_add_f32_e32 v253, v253, v239
	v_add_f32_e32 v254, v254, v240
	v_add_f32_e32 v255, v255, v241
	v_add_f32_e32 v224, v224, v242
	v_add_f32_e32 v225, v225, v243
	ds_bpermute_b32 v236, v235, v250
	ds_bpermute_b32 v237, v235, v251
	ds_bpermute_b32 v238, v235, v252
	ds_bpermute_b32 v239, v235, v253
	ds_bpermute_b32 v240, v235, v254
	ds_bpermute_b32 v241, v235, v255
	ds_bpermute_b32 v242, v235, v224
	ds_bpermute_b32 v243, v235, v225
	v_and_b32_e32 v0, 15, v180
	v_or_b32_e32 v0, s7, v0
	v_lshlrev_b32_e32 v0, 4, v0
	s_lshl_b32 s74, s53, 2
	v_add_u32_e32 v0, s74, v0
	s_ashr_i32 s7, s6, 31
	s_lshl_b64 s[4:5], s[6:7], 19
	s_add_u32 s4, s39, s4
	s_addc_u32 s5, s42, s5
	v_bfe_u32 v195, v180, 4, 2
	v_cmp_eq_u32_e64 s[40:41], 0, v195
	s_waitcnt lgkmcnt(0)
	v_add_f32_e32 v250, v250, v236
	v_add_f32_e32 v251, v251, v237
	v_add_f32_e32 v252, v252, v238
	v_add_f32_e32 v253, v253, v239
	v_add_f32_e32 v254, v254, v240
	v_add_f32_e32 v255, v255, v241
	v_add_f32_e32 v224, v224, v242
	v_add_f32_e32 v225, v225, v243
	v_readlane_b32 s44, v230, 7
	v_readlane_b32 s45, v230, 8
	s_and_saveexec_b64 s[2:3], s[40:41]
	global_store_dword v0, v250, s[4:5]
	global_store_dword v0, v251, s[4:5] offset:256
	global_store_dword v0, v252, s[4:5] offset:512
	global_store_dword v0, v253, s[4:5] offset:768
	global_store_dword v0, v254, s[4:5] offset:2048
	global_store_dword v0, v255, s[4:5] offset:2304
	global_store_dword v0, v224, s[4:5] offset:2560
	global_store_dword v0, v225, s[4:5] offset:2816
	s_branch .LBB0_1277
